# counted waits: a unit's last K iteration gets its own loop copy whose first two waits are vmcnt(8+P) (P = epilogue loads pre-issued just before it), so they no longer retire tile DMAs early
# baseline (speedup 1.0000x reference)
.Lc0s_final:
	s_add_i32 s62, s58, 0xfff80080
	s_and_b64 s[10:11], s[10:11], exec
	s_cselect_b32 s78, s54, s62
	s_cselect_b32 s62, s55, s60
	s_add_i32 s10, 0, 0x10000
	v_add_u32_e32 v0, s10, v157
	v_add_u32_e32 v147, s10, v158
	s_add_i32 s10, 0, 0x14000
	ds_read_b128 v[164:167], v0
	ds_read_b128 v[168:171], v0 offset:2048
	ds_read_b128 v[172:175], v147
	ds_read_b128 v[176:179], v147 offset:2048
	v_add_u32_e32 v0, s10, v157
	v_add_u32_e32 v147, s10, v158
	ds_read_b128 v[180:183], v0
	ds_read_b128 v[184:187], v0 offset:2048
	ds_read_b128 v[188:191], v147
	ds_read_b128 v[192:195], v147 offset:2048
	s_or_b32 s64, s78, 0x80
	s_or_b32 s65, s62, 0x80
	s_mov_b32 m0, s41
	ds_read_b128 v[196:199], v161
	ds_read_b128 v[204:207], v161 offset:2048
	ds_read_b128 v[208:211], v162
	ds_read_b128 v[212:215], v162 offset:2048
	ds_read_b128 v[216:219], v161 offset:4096
	ds_read_b128 v[220:223], v161 offset:6144
	ds_read_b128 v[224:227], v162 offset:4096
	ds_read_b128 v[228:231], v162 offset:6144
	buffer_load_dwordx4 v153, s[48:51], s58 offen lds
	s_mov_b32 m0, s42
	s_nop 0
	buffer_load_dwordx4 v155, s[48:51], s58 offen lds
	s_waitcnt vmcnt(16)
	s_waitcnt lgkmcnt(0)
	s_barrier
	s_waitcnt lgkmcnt(0)
	v_mfma_f32_16x16x32_f16 v[118:121], v[164:167], v[196:199], v[118:121]
	v_mfma_f32_16x16x32_f16 v[110:113], v[168:171], v[196:199], v[110:113]
	v_mfma_f32_16x16x32_f16 v[102:105], v[164:167], v[204:207], v[102:105]
	v_mfma_f32_16x16x32_f16 v[94:97], v[168:171], v[204:207], v[94:97]
	v_mfma_f32_16x16x32_f16 v[86:89], v[164:167], v[216:219], v[86:89]
	v_mfma_f32_16x16x32_f16 v[78:81], v[168:171], v[216:219], v[78:81]
	v_mfma_f32_16x16x32_f16 v[66:69], v[164:167], v[220:223], v[66:69]
	v_mfma_f32_16x16x32_f16 v[58:61], v[168:171], v[220:223], v[58:61]
	v_mfma_f32_16x16x32_f16 v[118:121], v[172:175], v[208:211], v[118:121]
	v_mfma_f32_16x16x32_f16 v[110:113], v[176:179], v[208:211], v[110:113]
	v_mfma_f32_16x16x32_f16 v[102:105], v[172:175], v[212:215], v[102:105]
	v_mfma_f32_16x16x32_f16 v[94:97], v[176:179], v[212:215], v[94:97]
	v_mfma_f32_16x16x32_f16 v[86:89], v[172:175], v[224:227], v[86:89]
	v_mfma_f32_16x16x32_f16 v[78:81], v[176:179], v[224:227], v[78:81]
	v_mfma_f32_16x16x32_f16 v[66:69], v[172:175], v[228:231], v[66:69]
	v_mfma_f32_16x16x32_f16 v[58:61], v[176:179], v[228:231], v[58:61]
	v_mfma_f32_16x16x32_f16 v[126:129], v[180:183], v[196:199], v[126:129]
	v_mfma_f32_16x16x32_f16 v[122:125], v[184:187], v[196:199], v[122:125]
	v_mfma_f32_16x16x32_f16 v[114:117], v[180:183], v[204:207], v[114:117]
	v_mfma_f32_16x16x32_f16 v[106:109], v[184:187], v[204:207], v[106:109]
	v_mfma_f32_16x16x32_f16 v[98:101], v[180:183], v[216:219], v[98:101]
	v_mfma_f32_16x16x32_f16 v[90:93], v[184:187], v[216:219], v[90:93]
	v_mfma_f32_16x16x32_f16 v[82:85], v[180:183], v[220:223], v[82:85]
	v_mfma_f32_16x16x32_f16 v[74:77], v[184:187], v[220:223], v[74:77]
	v_mfma_f32_16x16x32_f16 v[126:129], v[188:191], v[208:211], v[126:129]
	v_mfma_f32_16x16x32_f16 v[122:125], v[192:195], v[208:211], v[122:125]
	v_mfma_f32_16x16x32_f16 v[114:117], v[188:191], v[212:215], v[114:117]
	v_mfma_f32_16x16x32_f16 v[106:109], v[192:195], v[212:215], v[106:109]
	v_mfma_f32_16x16x32_f16 v[98:101], v[188:191], v[224:227], v[98:101]
	v_mfma_f32_16x16x32_f16 v[90:93], v[192:195], v[224:227], v[90:93]
	v_mfma_f32_16x16x32_f16 v[82:85], v[188:191], v[228:231], v[82:85]
	v_mfma_f32_16x16x32_f16 v[74:77], v[192:195], v[228:231], v[74:77]
	s_barrier
	s_mov_b32 s10, s50
	s_mov_b32 s11, s51
	ds_read_b128 v[196:199], v161 offset:16384
	ds_read_b128 v[204:207], v161 offset:18432
	ds_read_b128 v[208:211], v162 offset:16384
	ds_read_b128 v[212:215], v162 offset:18432
	ds_read_b128 v[216:219], v161 offset:20480
	ds_read_b128 v[220:223], v161 offset:22528
	ds_read_b128 v[224:227], v162 offset:20480
	ds_read_b128 v[228:231], v162 offset:22528
	s_add_i32 s81, s62, 0x80000
	s_waitcnt vmcnt(10)
	s_waitcnt lgkmcnt(0)
	s_barrier
	s_waitcnt lgkmcnt(0)
	v_mfma_f32_16x16x32_f16 v[54:57], v[164:167], v[196:199], v[54:57]
	v_mfma_f32_16x16x32_f16 v[46:49], v[168:171], v[196:199], v[46:49]
	v_mfma_f32_16x16x32_f16 v[38:41], v[164:167], v[204:207], v[38:41]
	v_mfma_f32_16x16x32_f16 v[30:33], v[168:171], v[204:207], v[30:33]
	v_mfma_f32_16x16x32_f16 v[22:25], v[164:167], v[216:219], v[22:25]
	v_mfma_f32_16x16x32_f16 v[14:17], v[168:171], v[216:219], v[14:17]
	v_mfma_f32_16x16x32_f16 v[6:9], v[164:167], v[220:223], v[6:9]
	v_mfma_f32_16x16x32_f16 v[2:5], v[168:171], v[220:223], v[2:5]
	v_mfma_f32_16x16x32_f16 v[54:57], v[172:175], v[208:211], v[54:57]
	v_mfma_f32_16x16x32_f16 v[46:49], v[176:179], v[208:211], v[46:49]
	v_mfma_f32_16x16x32_f16 v[38:41], v[172:175], v[212:215], v[38:41]
	v_mfma_f32_16x16x32_f16 v[30:33], v[176:179], v[212:215], v[30:33]
	v_mfma_f32_16x16x32_f16 v[22:25], v[172:175], v[224:227], v[22:25]
	v_mfma_f32_16x16x32_f16 v[14:17], v[176:179], v[224:227], v[14:17]
	v_mfma_f32_16x16x32_f16 v[6:9], v[172:175], v[228:231], v[6:9]
	v_mfma_f32_16x16x32_f16 v[2:5], v[176:179], v[228:231], v[2:5]
	v_mfma_f32_16x16x32_f16 v[70:73], v[180:183], v[196:199], v[70:73]
	v_mfma_f32_16x16x32_f16 v[62:65], v[184:187], v[196:199], v[62:65]
	v_mfma_f32_16x16x32_f16 v[50:53], v[180:183], v[204:207], v[50:53]
	v_mfma_f32_16x16x32_f16 v[42:45], v[184:187], v[204:207], v[42:45]
	v_mfma_f32_16x16x32_f16 v[34:37], v[180:183], v[216:219], v[34:37]
	v_mfma_f32_16x16x32_f16 v[26:29], v[184:187], v[216:219], v[26:29]
	v_mfma_f32_16x16x32_f16 v[18:21], v[180:183], v[220:223], v[18:21]
	v_mfma_f32_16x16x32_f16 v[10:13], v[184:187], v[220:223], v[10:13]
	v_mfma_f32_16x16x32_f16 v[70:73], v[188:191], v[208:211], v[70:73]
	v_mfma_f32_16x16x32_f16 v[62:65], v[192:195], v[208:211], v[62:65]
	v_mfma_f32_16x16x32_f16 v[50:53], v[188:191], v[212:215], v[50:53]
	v_mfma_f32_16x16x32_f16 v[42:45], v[192:195], v[212:215], v[42:45]
	v_mfma_f32_16x16x32_f16 v[34:37], v[188:191], v[224:227], v[34:37]
	v_mfma_f32_16x16x32_f16 v[26:29], v[192:195], v[224:227], v[26:29]
	v_mfma_f32_16x16x32_f16 v[18:21], v[188:191], v[228:231], v[18:21]
	v_mfma_f32_16x16x32_f16 v[10:13], v[192:195], v[228:231], v[10:13]
	s_barrier
	s_add_i32 s81, 0, 0x18000
	v_add_u32_e32 v0, s81, v157
	v_add_u32_e32 v147, s81, v158
	s_add_i32 s81, 0, 0x1c000
	ds_read_b128 v[164:167], v0
	ds_read_b128 v[168:171], v0 offset:2048
	ds_read_b128 v[172:175], v147
	ds_read_b128 v[176:179], v147 offset:2048
	v_add_u32_e32 v0, s81, v157
	v_add_u32_e32 v147, s81, v158
	ds_read_b128 v[180:183], v0
	ds_read_b128 v[184:187], v0 offset:2048
	ds_read_b128 v[188:191], v147
	ds_read_b128 v[192:195], v147 offset:2048
	s_add_i32 s78, s78, 0x80000
	ds_read_b128 v[196:199], v161 offset:32768
	ds_read_b128 v[204:207], v161 offset:34816
	ds_read_b128 v[208:211], v162 offset:32768
	ds_read_b128 v[212:215], v162 offset:34816
	ds_read_b128 v[216:219], v161 offset:36864
	ds_read_b128 v[220:223], v161 offset:38912
	ds_read_b128 v[224:227], v162 offset:36864
	ds_read_b128 v[228:231], v162 offset:38912
	s_waitcnt vmcnt(0)
	s_waitcnt lgkmcnt(0)
	s_barrier
	s_waitcnt lgkmcnt(0)
	v_mfma_f32_16x16x32_f16 v[118:121], v[164:167], v[196:199], v[118:121]
	v_mfma_f32_16x16x32_f16 v[110:113], v[168:171], v[196:199], v[110:113]
	v_mfma_f32_16x16x32_f16 v[102:105], v[164:167], v[204:207], v[102:105]
	v_mfma_f32_16x16x32_f16 v[94:97], v[168:171], v[204:207], v[94:97]
	v_mfma_f32_16x16x32_f16 v[86:89], v[164:167], v[216:219], v[86:89]
	v_mfma_f32_16x16x32_f16 v[78:81], v[168:171], v[216:219], v[78:81]
	v_mfma_f32_16x16x32_f16 v[66:69], v[164:167], v[220:223], v[66:69]
	v_mfma_f32_16x16x32_f16 v[58:61], v[168:171], v[220:223], v[58:61]
	v_mfma_f32_16x16x32_f16 v[118:121], v[172:175], v[208:211], v[118:121]
	v_mfma_f32_16x16x32_f16 v[110:113], v[176:179], v[208:211], v[110:113]
	v_mfma_f32_16x16x32_f16 v[102:105], v[172:175], v[212:215], v[102:105]
	v_mfma_f32_16x16x32_f16 v[94:97], v[176:179], v[212:215], v[94:97]
	v_mfma_f32_16x16x32_f16 v[86:89], v[172:175], v[224:227], v[86:89]
	v_mfma_f32_16x16x32_f16 v[78:81], v[176:179], v[224:227], v[78:81]
	v_mfma_f32_16x16x32_f16 v[66:69], v[172:175], v[228:231], v[66:69]
	v_mfma_f32_16x16x32_f16 v[58:61], v[176:179], v[228:231], v[58:61]
	v_mfma_f32_16x16x32_f16 v[126:129], v[180:183], v[196:199], v[126:129]
	v_mfma_f32_16x16x32_f16 v[122:125], v[184:187], v[196:199], v[122:125]
	v_mfma_f32_16x16x32_f16 v[114:117], v[180:183], v[204:207], v[114:117]
	v_mfma_f32_16x16x32_f16 v[106:109], v[184:187], v[204:207], v[106:109]
	v_mfma_f32_16x16x32_f16 v[98:101], v[180:183], v[216:219], v[98:101]
	v_mfma_f32_16x16x32_f16 v[90:93], v[184:187], v[216:219], v[90:93]
	v_mfma_f32_16x16x32_f16 v[82:85], v[180:183], v[220:223], v[82:85]
	v_mfma_f32_16x16x32_f16 v[74:77], v[184:187], v[220:223], v[74:77]
	v_mfma_f32_16x16x32_f16 v[126:129], v[188:191], v[208:211], v[126:129]
	v_mfma_f32_16x16x32_f16 v[122:125], v[192:195], v[208:211], v[122:125]
	v_mfma_f32_16x16x32_f16 v[114:117], v[188:191], v[212:215], v[114:117]
	v_mfma_f32_16x16x32_f16 v[106:109], v[192:195], v[212:215], v[106:109]
	v_mfma_f32_16x16x32_f16 v[98:101], v[188:191], v[224:227], v[98:101]
	v_mfma_f32_16x16x32_f16 v[90:93], v[192:195], v[224:227], v[90:93]
	v_mfma_f32_16x16x32_f16 v[82:85], v[188:191], v[228:231], v[82:85]
	v_mfma_f32_16x16x32_f16 v[74:77], v[192:195], v[228:231], v[74:77]
	s_barrier
	ds_read_b128 v[196:199], v161 offset:49152
	ds_read_b128 v[204:207], v161 offset:51200
	ds_read_b128 v[208:211], v162 offset:49152
	ds_read_b128 v[212:215], v162 offset:51200
	ds_read_b128 v[216:219], v161 offset:53248
	ds_read_b128 v[220:223], v161 offset:55296
	ds_read_b128 v[224:227], v162 offset:53248
	ds_read_b128 v[228:231], v162 offset:55296
	s_add_i32 s62, s62, 0x80080
	s_waitcnt vmcnt(0)
	s_waitcnt lgkmcnt(0)
	s_barrier
	s_waitcnt lgkmcnt(0)
	v_mfma_f32_16x16x32_f16 v[54:57], v[164:167], v[196:199], v[54:57]
	v_mfma_f32_16x16x32_f16 v[46:49], v[168:171], v[196:199], v[46:49]
	v_mfma_f32_16x16x32_f16 v[38:41], v[164:167], v[204:207], v[38:41]
	v_mfma_f32_16x16x32_f16 v[30:33], v[168:171], v[204:207], v[30:33]
	v_mfma_f32_16x16x32_f16 v[22:25], v[164:167], v[216:219], v[22:25]
	v_mfma_f32_16x16x32_f16 v[14:17], v[168:171], v[216:219], v[14:17]
	v_mfma_f32_16x16x32_f16 v[6:9], v[164:167], v[220:223], v[6:9]
	v_mfma_f32_16x16x32_f16 v[2:5], v[168:171], v[220:223], v[2:5]
	v_mfma_f32_16x16x32_f16 v[54:57], v[172:175], v[208:211], v[54:57]
	v_mfma_f32_16x16x32_f16 v[46:49], v[176:179], v[208:211], v[46:49]
	v_mfma_f32_16x16x32_f16 v[38:41], v[172:175], v[212:215], v[38:41]
	v_mfma_f32_16x16x32_f16 v[30:33], v[176:179], v[212:215], v[30:33]
	v_mfma_f32_16x16x32_f16 v[22:25], v[172:175], v[224:227], v[22:25]
	v_mfma_f32_16x16x32_f16 v[14:17], v[176:179], v[224:227], v[14:17]
	v_mfma_f32_16x16x32_f16 v[6:9], v[172:175], v[228:231], v[6:9]
	v_mfma_f32_16x16x32_f16 v[2:5], v[176:179], v[228:231], v[2:5]
	v_mfma_f32_16x16x32_f16 v[70:73], v[180:183], v[196:199], v[70:73]
	v_mfma_f32_16x16x32_f16 v[62:65], v[184:187], v[196:199], v[62:65]
	v_mfma_f32_16x16x32_f16 v[50:53], v[180:183], v[204:207], v[50:53]
	v_mfma_f32_16x16x32_f16 v[42:45], v[184:187], v[204:207], v[42:45]
	v_mfma_f32_16x16x32_f16 v[34:37], v[180:183], v[216:219], v[34:37]
	v_mfma_f32_16x16x32_f16 v[26:29], v[184:187], v[216:219], v[26:29]
	v_mfma_f32_16x16x32_f16 v[18:21], v[180:183], v[220:223], v[18:21]
	v_mfma_f32_16x16x32_f16 v[10:13], v[184:187], v[220:223], v[10:13]
	v_mfma_f32_16x16x32_f16 v[70:73], v[188:191], v[208:211], v[70:73]
	v_mfma_f32_16x16x32_f16 v[62:65], v[192:195], v[208:211], v[62:65]
	v_mfma_f32_16x16x32_f16 v[50:53], v[188:191], v[212:215], v[50:53]
	v_mfma_f32_16x16x32_f16 v[42:45], v[192:195], v[212:215], v[42:45]
	v_mfma_f32_16x16x32_f16 v[34:37], v[188:191], v[224:227], v[34:37]
	v_mfma_f32_16x16x32_f16 v[26:29], v[192:195], v[224:227], v[26:29]
	v_mfma_f32_16x16x32_f16 v[18:21], v[188:191], v[228:231], v[18:21]
	v_mfma_f32_16x16x32_f16 v[10:13], v[192:195], v[228:231], v[10:13]
	s_barrier
	s_branch .Lc0s_tail
.Lc0s_last:
	s_add_i32 s62, s58, 0xfff80080
	s_and_b64 s[10:11], s[10:11], exec
	s_cselect_b32 s78, s54, s62
	s_cselect_b32 s62, s55, s60
	s_add_i32 s10, 0, 0x10000
	v_add_u32_e32 v0, s10, v157
	v_add_u32_e32 v147, s10, v158
	s_add_i32 s10, 0, 0x14000
	ds_read_b128 v[164:167], v0
	ds_read_b128 v[168:171], v0 offset:2048
	ds_read_b128 v[172:175], v147
	ds_read_b128 v[176:179], v147 offset:2048
	v_add_u32_e32 v0, s10, v157
	v_add_u32_e32 v147, s10, v158
	ds_read_b128 v[180:183], v0
	ds_read_b128 v[184:187], v0 offset:2048
	ds_read_b128 v[188:191], v147
	ds_read_b128 v[192:195], v147 offset:2048
	s_or_b32 s64, s78, 0x80
	s_or_b32 s65, s62, 0x80
	s_mov_b32 m0, s41
	ds_read_b128 v[196:199], v161
	ds_read_b128 v[204:207], v161 offset:2048
	ds_read_b128 v[208:211], v162
	ds_read_b128 v[212:215], v162 offset:2048
	ds_read_b128 v[216:219], v161 offset:4096
	ds_read_b128 v[220:223], v161 offset:6144
	ds_read_b128 v[224:227], v162 offset:4096
	ds_read_b128 v[228:231], v162 offset:6144
	buffer_load_dwordx4 v153, s[48:51], s58 offen lds
	s_mov_b32 m0, s42
	s_nop 0
	buffer_load_dwordx4 v155, s[48:51], s58 offen lds
	s_waitcnt vmcnt(16)
	s_waitcnt lgkmcnt(0)
	s_barrier
	s_waitcnt lgkmcnt(0)
	v_mfma_f32_16x16x32_f16 v[118:121], v[164:167], v[196:199], v[118:121]
	v_mfma_f32_16x16x32_f16 v[110:113], v[168:171], v[196:199], v[110:113]
	v_mfma_f32_16x16x32_f16 v[102:105], v[164:167], v[204:207], v[102:105]
	v_mfma_f32_16x16x32_f16 v[94:97], v[168:171], v[204:207], v[94:97]
	v_mfma_f32_16x16x32_f16 v[86:89], v[164:167], v[216:219], v[86:89]
	v_mfma_f32_16x16x32_f16 v[78:81], v[168:171], v[216:219], v[78:81]
	v_mfma_f32_16x16x32_f16 v[66:69], v[164:167], v[220:223], v[66:69]
	v_mfma_f32_16x16x32_f16 v[58:61], v[168:171], v[220:223], v[58:61]
	v_mfma_f32_16x16x32_f16 v[118:121], v[172:175], v[208:211], v[118:121]
	v_mfma_f32_16x16x32_f16 v[110:113], v[176:179], v[208:211], v[110:113]
	v_mfma_f32_16x16x32_f16 v[102:105], v[172:175], v[212:215], v[102:105]
	v_mfma_f32_16x16x32_f16 v[94:97], v[176:179], v[212:215], v[94:97]
	v_mfma_f32_16x16x32_f16 v[86:89], v[172:175], v[224:227], v[86:89]
	v_mfma_f32_16x16x32_f16 v[78:81], v[176:179], v[224:227], v[78:81]
	v_mfma_f32_16x16x32_f16 v[66:69], v[172:175], v[228:231], v[66:69]
	v_mfma_f32_16x16x32_f16 v[58:61], v[176:179], v[228:231], v[58:61]
	v_mfma_f32_16x16x32_f16 v[126:129], v[180:183], v[196:199], v[126:129]
	v_mfma_f32_16x16x32_f16 v[122:125], v[184:187], v[196:199], v[122:125]
	v_mfma_f32_16x16x32_f16 v[114:117], v[180:183], v[204:207], v[114:117]
	v_mfma_f32_16x16x32_f16 v[106:109], v[184:187], v[204:207], v[106:109]
	v_mfma_f32_16x16x32_f16 v[98:101], v[180:183], v[216:219], v[98:101]
	v_mfma_f32_16x16x32_f16 v[90:93], v[184:187], v[216:219], v[90:93]
	v_mfma_f32_16x16x32_f16 v[82:85], v[180:183], v[220:223], v[82:85]
	v_mfma_f32_16x16x32_f16 v[74:77], v[184:187], v[220:223], v[74:77]
	v_mfma_f32_16x16x32_f16 v[126:129], v[188:191], v[208:211], v[126:129]
	v_mfma_f32_16x16x32_f16 v[122:125], v[192:195], v[208:211], v[122:125]
	v_mfma_f32_16x16x32_f16 v[114:117], v[188:191], v[212:215], v[114:117]
	v_mfma_f32_16x16x32_f16 v[106:109], v[192:195], v[212:215], v[106:109]
	v_mfma_f32_16x16x32_f16 v[98:101], v[188:191], v[224:227], v[98:101]
	v_mfma_f32_16x16x32_f16 v[90:93], v[192:195], v[224:227], v[90:93]
	v_mfma_f32_16x16x32_f16 v[82:85], v[188:191], v[228:231], v[82:85]
	v_mfma_f32_16x16x32_f16 v[74:77], v[192:195], v[228:231], v[74:77]
	s_barrier
	s_mov_b32 m0, s26
	s_mov_b32 s10, s50
	s_mov_b32 s11, s51
	ds_read_b128 v[196:199], v161 offset:16384
	ds_read_b128 v[204:207], v161 offset:18432
	ds_read_b128 v[208:211], v162 offset:16384
	ds_read_b128 v[212:215], v162 offset:18432
	ds_read_b128 v[216:219], v161 offset:20480
	ds_read_b128 v[220:223], v161 offset:22528
	ds_read_b128 v[224:227], v162 offset:20480
	ds_read_b128 v[228:231], v162 offset:22528
	buffer_load_dwordx4 v154, s[8:11], s62 offen lds
	s_mov_b32 m0, s27
	s_add_i32 s81, s62, 0x80000
	buffer_load_dwordx4 v156, s[8:11], s62 offen lds
	s_mov_b32 m0, s28
	s_nop 0
	buffer_load_dwordx4 v154, s[8:11], s81 offen lds
	s_mov_b32 m0, s29
	s_nop 0
	buffer_load_dwordx4 v156, s[8:11], s81 offen lds
	s_mov_b32 m0, s3
	s_nop 0
	buffer_load_dwordx4 v153, s[48:51], s78 offen lds
	s_mov_b32 m0, s30
	s_nop 0
	buffer_load_dwordx4 v155, s[48:51], s78 offen lds
	s_waitcnt vmcnt(16)
	s_waitcnt lgkmcnt(0)
	s_barrier
	s_waitcnt lgkmcnt(0)
	v_mfma_f32_16x16x32_f16 v[54:57], v[164:167], v[196:199], v[54:57]
	v_mfma_f32_16x16x32_f16 v[46:49], v[168:171], v[196:199], v[46:49]
	v_mfma_f32_16x16x32_f16 v[38:41], v[164:167], v[204:207], v[38:41]
	v_mfma_f32_16x16x32_f16 v[30:33], v[168:171], v[204:207], v[30:33]
	v_mfma_f32_16x16x32_f16 v[22:25], v[164:167], v[216:219], v[22:25]
	v_mfma_f32_16x16x32_f16 v[14:17], v[168:171], v[216:219], v[14:17]
	v_mfma_f32_16x16x32_f16 v[6:9], v[164:167], v[220:223], v[6:9]
	v_mfma_f32_16x16x32_f16 v[2:5], v[168:171], v[220:223], v[2:5]
	v_mfma_f32_16x16x32_f16 v[54:57], v[172:175], v[208:211], v[54:57]
	v_mfma_f32_16x16x32_f16 v[46:49], v[176:179], v[208:211], v[46:49]
	v_mfma_f32_16x16x32_f16 v[38:41], v[172:175], v[212:215], v[38:41]
	v_mfma_f32_16x16x32_f16 v[30:33], v[176:179], v[212:215], v[30:33]
	v_mfma_f32_16x16x32_f16 v[22:25], v[172:175], v[224:227], v[22:25]
	v_mfma_f32_16x16x32_f16 v[14:17], v[176:179], v[224:227], v[14:17]
	v_mfma_f32_16x16x32_f16 v[6:9], v[172:175], v[228:231], v[6:9]
	v_mfma_f32_16x16x32_f16 v[2:5], v[176:179], v[228:231], v[2:5]
	v_mfma_f32_16x16x32_f16 v[70:73], v[180:183], v[196:199], v[70:73]
	v_mfma_f32_16x16x32_f16 v[62:65], v[184:187], v[196:199], v[62:65]
	v_mfma_f32_16x16x32_f16 v[50:53], v[180:183], v[204:207], v[50:53]
	v_mfma_f32_16x16x32_f16 v[42:45], v[184:187], v[204:207], v[42:45]
	v_mfma_f32_16x16x32_f16 v[34:37], v[180:183], v[216:219], v[34:37]
	v_mfma_f32_16x16x32_f16 v[26:29], v[184:187], v[216:219], v[26:29]
	v_mfma_f32_16x16x32_f16 v[18:21], v[180:183], v[220:223], v[18:21]
	v_mfma_f32_16x16x32_f16 v[10:13], v[184:187], v[220:223], v[10:13]
	v_mfma_f32_16x16x32_f16 v[70:73], v[188:191], v[208:211], v[70:73]
	v_mfma_f32_16x16x32_f16 v[62:65], v[192:195], v[208:211], v[62:65]
	v_mfma_f32_16x16x32_f16 v[50:53], v[188:191], v[212:215], v[50:53]
	v_mfma_f32_16x16x32_f16 v[42:45], v[192:195], v[212:215], v[42:45]
	v_mfma_f32_16x16x32_f16 v[34:37], v[188:191], v[224:227], v[34:37]
	v_mfma_f32_16x16x32_f16 v[26:29], v[192:195], v[224:227], v[26:29]
	v_mfma_f32_16x16x32_f16 v[18:21], v[188:191], v[228:231], v[18:21]
	v_mfma_f32_16x16x32_f16 v[10:13], v[192:195], v[228:231], v[10:13]
	s_barrier
	s_add_i32 s81, 0, 0x18000
	v_add_u32_e32 v0, s81, v157
	v_add_u32_e32 v147, s81, v158
	s_add_i32 s81, 0, 0x1c000
	ds_read_b128 v[164:167], v0
	ds_read_b128 v[168:171], v0 offset:2048
	ds_read_b128 v[172:175], v147
	ds_read_b128 v[176:179], v147 offset:2048
	v_add_u32_e32 v0, s81, v157
	v_add_u32_e32 v147, s81, v158
	ds_read_b128 v[180:183], v0
	ds_read_b128 v[184:187], v0 offset:2048
	ds_read_b128 v[188:191], v147
	ds_read_b128 v[192:195], v147 offset:2048
	s_add_i32 s78, s78, 0x80000
	s_mov_b32 m0, s31
	ds_read_b128 v[196:199], v161 offset:32768
	ds_read_b128 v[204:207], v161 offset:34816
	ds_read_b128 v[208:211], v162 offset:32768
	ds_read_b128 v[212:215], v162 offset:34816
	ds_read_b128 v[216:219], v161 offset:36864
	ds_read_b128 v[220:223], v161 offset:38912
	ds_read_b128 v[224:227], v162 offset:36864
	ds_read_b128 v[228:231], v162 offset:38912
	buffer_load_dwordx4 v153, s[48:51], s78 offen lds
	s_mov_b32 m0, s34
	s_nop 0
	buffer_load_dwordx4 v155, s[48:51], s78 offen lds
	s_waitcnt vmcnt(8)
	s_waitcnt lgkmcnt(0)
	s_barrier
	s_waitcnt lgkmcnt(0)
	v_mfma_f32_16x16x32_f16 v[118:121], v[164:167], v[196:199], v[118:121]
	v_mfma_f32_16x16x32_f16 v[110:113], v[168:171], v[196:199], v[110:113]
	v_mfma_f32_16x16x32_f16 v[102:105], v[164:167], v[204:207], v[102:105]
	v_mfma_f32_16x16x32_f16 v[94:97], v[168:171], v[204:207], v[94:97]
	v_mfma_f32_16x16x32_f16 v[86:89], v[164:167], v[216:219], v[86:89]
	v_mfma_f32_16x16x32_f16 v[78:81], v[168:171], v[216:219], v[78:81]
	v_mfma_f32_16x16x32_f16 v[66:69], v[164:167], v[220:223], v[66:69]
	v_mfma_f32_16x16x32_f16 v[58:61], v[168:171], v[220:223], v[58:61]
	v_mfma_f32_16x16x32_f16 v[118:121], v[172:175], v[208:211], v[118:121]
	v_mfma_f32_16x16x32_f16 v[110:113], v[176:179], v[208:211], v[110:113]
	v_mfma_f32_16x16x32_f16 v[102:105], v[172:175], v[212:215], v[102:105]
	v_mfma_f32_16x16x32_f16 v[94:97], v[176:179], v[212:215], v[94:97]
	v_mfma_f32_16x16x32_f16 v[86:89], v[172:175], v[224:227], v[86:89]
	v_mfma_f32_16x16x32_f16 v[78:81], v[176:179], v[224:227], v[78:81]
	v_mfma_f32_16x16x32_f16 v[66:69], v[172:175], v[228:231], v[66:69]
	v_mfma_f32_16x16x32_f16 v[58:61], v[176:179], v[228:231], v[58:61]
	v_mfma_f32_16x16x32_f16 v[126:129], v[180:183], v[196:199], v[126:129]
	v_mfma_f32_16x16x32_f16 v[122:125], v[184:187], v[196:199], v[122:125]
	v_mfma_f32_16x16x32_f16 v[114:117], v[180:183], v[204:207], v[114:117]
	v_mfma_f32_16x16x32_f16 v[106:109], v[184:187], v[204:207], v[106:109]
	v_mfma_f32_16x16x32_f16 v[98:101], v[180:183], v[216:219], v[98:101]
	v_mfma_f32_16x16x32_f16 v[90:93], v[184:187], v[216:219], v[90:93]
	v_mfma_f32_16x16x32_f16 v[82:85], v[180:183], v[220:223], v[82:85]
	v_mfma_f32_16x16x32_f16 v[74:77], v[184:187], v[220:223], v[74:77]
	v_mfma_f32_16x16x32_f16 v[126:129], v[188:191], v[208:211], v[126:129]
	v_mfma_f32_16x16x32_f16 v[122:125], v[192:195], v[208:211], v[122:125]
	v_mfma_f32_16x16x32_f16 v[114:117], v[188:191], v[212:215], v[114:117]
	v_mfma_f32_16x16x32_f16 v[106:109], v[192:195], v[212:215], v[106:109]
	v_mfma_f32_16x16x32_f16 v[98:101], v[188:191], v[224:227], v[98:101]
	v_mfma_f32_16x16x32_f16 v[90:93], v[192:195], v[224:227], v[90:93]
	v_mfma_f32_16x16x32_f16 v[82:85], v[188:191], v[228:231], v[82:85]
	v_mfma_f32_16x16x32_f16 v[74:77], v[192:195], v[228:231], v[74:77]
	s_barrier
	s_mov_b32 m0, s35
	ds_read_b128 v[196:199], v161 offset:49152
	ds_read_b128 v[204:207], v161 offset:51200
	ds_read_b128 v[208:211], v162 offset:49152
	ds_read_b128 v[212:215], v162 offset:51200
	ds_read_b128 v[216:219], v161 offset:53248
	ds_read_b128 v[220:223], v161 offset:55296
	ds_read_b128 v[224:227], v162 offset:53248
	ds_read_b128 v[228:231], v162 offset:55296
	buffer_load_dwordx4 v154, s[8:11], s65 offen lds
	s_mov_b32 m0, s36
	s_add_i32 s62, s62, 0x80080
	buffer_load_dwordx4 v156, s[8:11], s65 offen lds
	s_mov_b32 m0, s39
	s_nop 0
	buffer_load_dwordx4 v154, s[8:11], s62 offen lds
	s_mov_b32 m0, s40
	s_nop 0
	buffer_load_dwordx4 v156, s[8:11], s62 offen lds
	s_mov_b32 m0, s37
	s_nop 0
	buffer_load_dwordx4 v153, s[48:51], s64 offen lds
	s_mov_b32 m0, s38
	s_nop 0
	buffer_load_dwordx4 v155, s[48:51], s64 offen lds
	s_waitcnt vmcnt(8)
	s_waitcnt lgkmcnt(0)
	s_barrier
	s_waitcnt lgkmcnt(0)
	v_mfma_f32_16x16x32_f16 v[54:57], v[164:167], v[196:199], v[54:57]
	v_mfma_f32_16x16x32_f16 v[46:49], v[168:171], v[196:199], v[46:49]
	v_mfma_f32_16x16x32_f16 v[38:41], v[164:167], v[204:207], v[38:41]
	v_mfma_f32_16x16x32_f16 v[30:33], v[168:171], v[204:207], v[30:33]
	v_mfma_f32_16x16x32_f16 v[22:25], v[164:167], v[216:219], v[22:25]
	v_mfma_f32_16x16x32_f16 v[14:17], v[168:171], v[216:219], v[14:17]
	v_mfma_f32_16x16x32_f16 v[6:9], v[164:167], v[220:223], v[6:9]
	v_mfma_f32_16x16x32_f16 v[2:5], v[168:171], v[220:223], v[2:5]
	v_mfma_f32_16x16x32_f16 v[54:57], v[172:175], v[208:211], v[54:57]
	v_mfma_f32_16x16x32_f16 v[46:49], v[176:179], v[208:211], v[46:49]
	v_mfma_f32_16x16x32_f16 v[38:41], v[172:175], v[212:215], v[38:41]
	v_mfma_f32_16x16x32_f16 v[30:33], v[176:179], v[212:215], v[30:33]
	v_mfma_f32_16x16x32_f16 v[22:25], v[172:175], v[224:227], v[22:25]
	v_mfma_f32_16x16x32_f16 v[14:17], v[176:179], v[224:227], v[14:17]
	v_mfma_f32_16x16x32_f16 v[6:9], v[172:175], v[228:231], v[6:9]
	v_mfma_f32_16x16x32_f16 v[2:5], v[176:179], v[228:231], v[2:5]
	v_mfma_f32_16x16x32_f16 v[70:73], v[180:183], v[196:199], v[70:73]
	v_mfma_f32_16x16x32_f16 v[62:65], v[184:187], v[196:199], v[62:65]
	v_mfma_f32_16x16x32_f16 v[50:53], v[180:183], v[204:207], v[50:53]
	v_mfma_f32_16x16x32_f16 v[42:45], v[184:187], v[204:207], v[42:45]
	v_mfma_f32_16x16x32_f16 v[34:37], v[180:183], v[216:219], v[34:37]
	v_mfma_f32_16x16x32_f16 v[26:29], v[184:187], v[216:219], v[26:29]
	v_mfma_f32_16x16x32_f16 v[18:21], v[180:183], v[220:223], v[18:21]
	v_mfma_f32_16x16x32_f16 v[10:13], v[184:187], v[220:223], v[10:13]
	v_mfma_f32_16x16x32_f16 v[70:73], v[188:191], v[208:211], v[70:73]
	v_mfma_f32_16x16x32_f16 v[62:65], v[192:195], v[208:211], v[62:65]
	v_mfma_f32_16x16x32_f16 v[50:53], v[188:191], v[212:215], v[50:53]
	v_mfma_f32_16x16x32_f16 v[42:45], v[192:195], v[212:215], v[42:45]
	v_mfma_f32_16x16x32_f16 v[34:37], v[188:191], v[224:227], v[34:37]
	v_mfma_f32_16x16x32_f16 v[26:29], v[192:195], v[224:227], v[26:29]
	v_mfma_f32_16x16x32_f16 v[18:21], v[188:191], v[228:231], v[18:21]
	v_mfma_f32_16x16x32_f16 v[10:13], v[192:195], v[228:231], v[10:13]
	s_barrier
	s_branch .Lc0s_tail
.LBB0_142:
	s_cmp_eq_u32 s61, -2
	s_cbranch_scc1 .Lc0s_first
	s_cmp_eq_u32 s61, 28
	s_cbranch_scc0 .Lc0s_norm
	s_cmp_eq_u64 s[4:5], 0
	s_cbranch_scc1 .Lc0s_final
	s_branch .Lc0s_last
.Lc0s_norm:
	s_add_i32 s62, s58, 0xfff80080
	s_and_b64 s[10:11], s[10:11], exec
	s_cselect_b32 s78, s54, s62
	s_cselect_b32 s62, s55, s60
	s_add_i32 s10, 0, 0x10000
	v_add_u32_e32 v0, s10, v157
	v_add_u32_e32 v147, s10, v158
	s_add_i32 s10, 0, 0x14000
	ds_read_b128 v[164:167], v0
	ds_read_b128 v[168:171], v0 offset:2048
	ds_read_b128 v[172:175], v147
	ds_read_b128 v[176:179], v147 offset:2048
	v_add_u32_e32 v0, s10, v157
	v_add_u32_e32 v147, s10, v158
	ds_read_b128 v[180:183], v0
	ds_read_b128 v[184:187], v0 offset:2048
	ds_read_b128 v[188:191], v147
	ds_read_b128 v[192:195], v147 offset:2048
	s_or_b32 s64, s78, 0x80
	s_or_b32 s65, s62, 0x80
	s_mov_b32 m0, s41
	ds_read_b128 v[196:199], v161
	ds_read_b128 v[204:207], v161 offset:2048
	ds_read_b128 v[208:211], v162
	ds_read_b128 v[212:215], v162 offset:2048
	ds_read_b128 v[216:219], v161 offset:4096
	ds_read_b128 v[220:223], v161 offset:6144
	ds_read_b128 v[224:227], v162 offset:4096
	ds_read_b128 v[228:231], v162 offset:6144
	buffer_load_dwordx4 v153, s[48:51], s58 offen lds
	s_mov_b32 m0, s42
	s_nop 0
	buffer_load_dwordx4 v155, s[48:51], s58 offen lds
	s_waitcnt vmcnt(8)
	s_waitcnt lgkmcnt(0)
	s_barrier
	s_waitcnt lgkmcnt(0)
	v_mfma_f32_16x16x32_f16 v[118:121], v[164:167], v[196:199], v[118:121]
	v_mfma_f32_16x16x32_f16 v[110:113], v[168:171], v[196:199], v[110:113]
	v_mfma_f32_16x16x32_f16 v[102:105], v[164:167], v[204:207], v[102:105]
	v_mfma_f32_16x16x32_f16 v[94:97], v[168:171], v[204:207], v[94:97]
	v_mfma_f32_16x16x32_f16 v[86:89], v[164:167], v[216:219], v[86:89]
	v_mfma_f32_16x16x32_f16 v[78:81], v[168:171], v[216:219], v[78:81]
	v_mfma_f32_16x16x32_f16 v[66:69], v[164:167], v[220:223], v[66:69]
	v_mfma_f32_16x16x32_f16 v[58:61], v[168:171], v[220:223], v[58:61]
	v_mfma_f32_16x16x32_f16 v[118:121], v[172:175], v[208:211], v[118:121]
	v_mfma_f32_16x16x32_f16 v[110:113], v[176:179], v[208:211], v[110:113]
	v_mfma_f32_16x16x32_f16 v[102:105], v[172:175], v[212:215], v[102:105]
	v_mfma_f32_16x16x32_f16 v[94:97], v[176:179], v[212:215], v[94:97]
	v_mfma_f32_16x16x32_f16 v[86:89], v[172:175], v[224:227], v[86:89]
	v_mfma_f32_16x16x32_f16 v[78:81], v[176:179], v[224:227], v[78:81]
	v_mfma_f32_16x16x32_f16 v[66:69], v[172:175], v[228:231], v[66:69]
	v_mfma_f32_16x16x32_f16 v[58:61], v[176:179], v[228:231], v[58:61]
	v_mfma_f32_16x16x32_f16 v[126:129], v[180:183], v[196:199], v[126:129]
	v_mfma_f32_16x16x32_f16 v[122:125], v[184:187], v[196:199], v[122:125]
	v_mfma_f32_16x16x32_f16 v[114:117], v[180:183], v[204:207], v[114:117]
	v_mfma_f32_16x16x32_f16 v[106:109], v[184:187], v[204:207], v[106:109]
	v_mfma_f32_16x16x32_f16 v[98:101], v[180:183], v[216:219], v[98:101]
	v_mfma_f32_16x16x32_f16 v[90:93], v[184:187], v[216:219], v[90:93]
	v_mfma_f32_16x16x32_f16 v[82:85], v[180:183], v[220:223], v[82:85]
	v_mfma_f32_16x16x32_f16 v[74:77], v[184:187], v[220:223], v[74:77]
	v_mfma_f32_16x16x32_f16 v[126:129], v[188:191], v[208:211], v[126:129]
	v_mfma_f32_16x16x32_f16 v[122:125], v[192:195], v[208:211], v[122:125]
	v_mfma_f32_16x16x32_f16 v[114:117], v[188:191], v[212:215], v[114:117]
	v_mfma_f32_16x16x32_f16 v[106:109], v[192:195], v[212:215], v[106:109]
	v_mfma_f32_16x16x32_f16 v[98:101], v[188:191], v[224:227], v[98:101]
	v_mfma_f32_16x16x32_f16 v[90:93], v[192:195], v[224:227], v[90:93]
	v_mfma_f32_16x16x32_f16 v[82:85], v[188:191], v[228:231], v[82:85]
	v_mfma_f32_16x16x32_f16 v[74:77], v[192:195], v[228:231], v[74:77]
	s_barrier
	s_mov_b32 m0, s26
	s_mov_b32 s10, s50
	s_mov_b32 s11, s51
	ds_read_b128 v[196:199], v161 offset:16384
	ds_read_b128 v[204:207], v161 offset:18432
	ds_read_b128 v[208:211], v162 offset:16384
	ds_read_b128 v[212:215], v162 offset:18432
	ds_read_b128 v[216:219], v161 offset:20480
	ds_read_b128 v[220:223], v161 offset:22528
	ds_read_b128 v[224:227], v162 offset:20480
	ds_read_b128 v[228:231], v162 offset:22528
	buffer_load_dwordx4 v154, s[8:11], s62 offen lds
	s_mov_b32 m0, s27
	s_add_i32 s81, s62, 0x80000
	buffer_load_dwordx4 v156, s[8:11], s62 offen lds
	s_mov_b32 m0, s28
	s_nop 0
	buffer_load_dwordx4 v154, s[8:11], s81 offen lds
	s_mov_b32 m0, s29
	s_nop 0
	buffer_load_dwordx4 v156, s[8:11], s81 offen lds
	s_mov_b32 m0, s3
	s_nop 0
	buffer_load_dwordx4 v153, s[48:51], s78 offen lds
	s_mov_b32 m0, s30
	s_nop 0
	buffer_load_dwordx4 v155, s[48:51], s78 offen lds
	s_waitcnt vmcnt(8)
	s_waitcnt lgkmcnt(0)
	s_barrier
	s_waitcnt lgkmcnt(0)
	v_mfma_f32_16x16x32_f16 v[54:57], v[164:167], v[196:199], v[54:57]
	v_mfma_f32_16x16x32_f16 v[46:49], v[168:171], v[196:199], v[46:49]
	v_mfma_f32_16x16x32_f16 v[38:41], v[164:167], v[204:207], v[38:41]
	v_mfma_f32_16x16x32_f16 v[30:33], v[168:171], v[204:207], v[30:33]
	v_mfma_f32_16x16x32_f16 v[22:25], v[164:167], v[216:219], v[22:25]
	v_mfma_f32_16x16x32_f16 v[14:17], v[168:171], v[216:219], v[14:17]
	v_mfma_f32_16x16x32_f16 v[6:9], v[164:167], v[220:223], v[6:9]
	v_mfma_f32_16x16x32_f16 v[2:5], v[168:171], v[220:223], v[2:5]
	v_mfma_f32_16x16x32_f16 v[54:57], v[172:175], v[208:211], v[54:57]
	v_mfma_f32_16x16x32_f16 v[46:49], v[176:179], v[208:211], v[46:49]
	v_mfma_f32_16x16x32_f16 v[38:41], v[172:175], v[212:215], v[38:41]
	v_mfma_f32_16x16x32_f16 v[30:33], v[176:179], v[212:215], v[30:33]
	v_mfma_f32_16x16x32_f16 v[22:25], v[172:175], v[224:227], v[22:25]
	v_mfma_f32_16x16x32_f16 v[14:17], v[176:179], v[224:227], v[14:17]
	v_mfma_f32_16x16x32_f16 v[6:9], v[172:175], v[228:231], v[6:9]
	v_mfma_f32_16x16x32_f16 v[2:5], v[176:179], v[228:231], v[2:5]
	v_mfma_f32_16x16x32_f16 v[70:73], v[180:183], v[196:199], v[70:73]
	v_mfma_f32_16x16x32_f16 v[62:65], v[184:187], v[196:199], v[62:65]
	v_mfma_f32_16x16x32_f16 v[50:53], v[180:183], v[204:207], v[50:53]
	v_mfma_f32_16x16x32_f16 v[42:45], v[184:187], v[204:207], v[42:45]
	v_mfma_f32_16x16x32_f16 v[34:37], v[180:183], v[216:219], v[34:37]
	v_mfma_f32_16x16x32_f16 v[26:29], v[184:187], v[216:219], v[26:29]
	v_mfma_f32_16x16x32_f16 v[18:21], v[180:183], v[220:223], v[18:21]
	v_mfma_f32_16x16x32_f16 v[10:13], v[184:187], v[220:223], v[10:13]
	v_mfma_f32_16x16x32_f16 v[70:73], v[188:191], v[208:211], v[70:73]
	v_mfma_f32_16x16x32_f16 v[62:65], v[192:195], v[208:211], v[62:65]
	v_mfma_f32_16x16x32_f16 v[50:53], v[188:191], v[212:215], v[50:53]
	v_mfma_f32_16x16x32_f16 v[42:45], v[192:195], v[212:215], v[42:45]
	v_mfma_f32_16x16x32_f16 v[34:37], v[188:191], v[224:227], v[34:37]
	v_mfma_f32_16x16x32_f16 v[26:29], v[192:195], v[224:227], v[26:29]
	v_mfma_f32_16x16x32_f16 v[18:21], v[188:191], v[228:231], v[18:21]
	v_mfma_f32_16x16x32_f16 v[10:13], v[192:195], v[228:231], v[10:13]
	s_barrier
	s_add_i32 s81, 0, 0x18000
	v_add_u32_e32 v0, s81, v157
	v_add_u32_e32 v147, s81, v158
	s_add_i32 s81, 0, 0x1c000
	ds_read_b128 v[164:167], v0
	ds_read_b128 v[168:171], v0 offset:2048
	ds_read_b128 v[172:175], v147
	ds_read_b128 v[176:179], v147 offset:2048
	v_add_u32_e32 v0, s81, v157
	v_add_u32_e32 v147, s81, v158
	ds_read_b128 v[180:183], v0
	ds_read_b128 v[184:187], v0 offset:2048
	ds_read_b128 v[188:191], v147
	ds_read_b128 v[192:195], v147 offset:2048
	s_add_i32 s78, s78, 0x80000
	s_mov_b32 m0, s31
	ds_read_b128 v[196:199], v161 offset:32768
	ds_read_b128 v[204:207], v161 offset:34816
	ds_read_b128 v[208:211], v162 offset:32768
	ds_read_b128 v[212:215], v162 offset:34816
	ds_read_b128 v[216:219], v161 offset:36864
	ds_read_b128 v[220:223], v161 offset:38912
	ds_read_b128 v[224:227], v162 offset:36864
	ds_read_b128 v[228:231], v162 offset:38912
	buffer_load_dwordx4 v153, s[48:51], s78 offen lds
	s_mov_b32 m0, s34
	s_nop 0
	buffer_load_dwordx4 v155, s[48:51], s78 offen lds
	s_waitcnt vmcnt(8)
	s_waitcnt lgkmcnt(0)
	s_barrier
	s_waitcnt lgkmcnt(0)
	v_mfma_f32_16x16x32_f16 v[118:121], v[164:167], v[196:199], v[118:121]
	v_mfma_f32_16x16x32_f16 v[110:113], v[168:171], v[196:199], v[110:113]
	v_mfma_f32_16x16x32_f16 v[102:105], v[164:167], v[204:207], v[102:105]
	v_mfma_f32_16x16x32_f16 v[94:97], v[168:171], v[204:207], v[94:97]
	v_mfma_f32_16x16x32_f16 v[86:89], v[164:167], v[216:219], v[86:89]
	v_mfma_f32_16x16x32_f16 v[78:81], v[168:171], v[216:219], v[78:81]
	v_mfma_f32_16x16x32_f16 v[66:69], v[164:167], v[220:223], v[66:69]
	v_mfma_f32_16x16x32_f16 v[58:61], v[168:171], v[220:223], v[58:61]
	v_mfma_f32_16x16x32_f16 v[118:121], v[172:175], v[208:211], v[118:121]
	v_mfma_f32_16x16x32_f16 v[110:113], v[176:179], v[208:211], v[110:113]
	v_mfma_f32_16x16x32_f16 v[102:105], v[172:175], v[212:215], v[102:105]
	v_mfma_f32_16x16x32_f16 v[94:97], v[176:179], v[212:215], v[94:97]
	v_mfma_f32_16x16x32_f16 v[86:89], v[172:175], v[224:227], v[86:89]
	v_mfma_f32_16x16x32_f16 v[78:81], v[176:179], v[224:227], v[78:81]
	v_mfma_f32_16x16x32_f16 v[66:69], v[172:175], v[228:231], v[66:69]
	v_mfma_f32_16x16x32_f16 v[58:61], v[176:179], v[228:231], v[58:61]
	v_mfma_f32_16x16x32_f16 v[126:129], v[180:183], v[196:199], v[126:129]
	v_mfma_f32_16x16x32_f16 v[122:125], v[184:187], v[196:199], v[122:125]
	v_mfma_f32_16x16x32_f16 v[114:117], v[180:183], v[204:207], v[114:117]
	v_mfma_f32_16x16x32_f16 v[106:109], v[184:187], v[204:207], v[106:109]
	v_mfma_f32_16x16x32_f16 v[98:101], v[180:183], v[216:219], v[98:101]
	v_mfma_f32_16x16x32_f16 v[90:93], v[184:187], v[216:219], v[90:93]
	v_mfma_f32_16x16x32_f16 v[82:85], v[180:183], v[220:223], v[82:85]
	v_mfma_f32_16x16x32_f16 v[74:77], v[184:187], v[220:223], v[74:77]
	v_mfma_f32_16x16x32_f16 v[126:129], v[188:191], v[208:211], v[126:129]
	v_mfma_f32_16x16x32_f16 v[122:125], v[192:195], v[208:211], v[122:125]
	v_mfma_f32_16x16x32_f16 v[114:117], v[188:191], v[212:215], v[114:117]
	v_mfma_f32_16x16x32_f16 v[106:109], v[192:195], v[212:215], v[106:109]
	v_mfma_f32_16x16x32_f16 v[98:101], v[188:191], v[224:227], v[98:101]
	v_mfma_f32_16x16x32_f16 v[90:93], v[192:195], v[224:227], v[90:93]
	v_mfma_f32_16x16x32_f16 v[82:85], v[188:191], v[228:231], v[82:85]
	v_mfma_f32_16x16x32_f16 v[74:77], v[192:195], v[228:231], v[74:77]
	s_barrier
	s_mov_b32 m0, s35
	ds_read_b128 v[196:199], v161 offset:49152
	ds_read_b128 v[204:207], v161 offset:51200
	ds_read_b128 v[208:211], v162 offset:49152
	ds_read_b128 v[212:215], v162 offset:51200
	ds_read_b128 v[216:219], v161 offset:53248
	ds_read_b128 v[220:223], v161 offset:55296
	ds_read_b128 v[224:227], v162 offset:53248
	ds_read_b128 v[228:231], v162 offset:55296
	buffer_load_dwordx4 v154, s[8:11], s65 offen lds
	s_mov_b32 m0, s36
	s_add_i32 s62, s62, 0x80080
	buffer_load_dwordx4 v156, s[8:11], s65 offen lds
	s_mov_b32 m0, s39
	s_nop 0
	buffer_load_dwordx4 v154, s[8:11], s62 offen lds
	s_mov_b32 m0, s40
	s_nop 0
	buffer_load_dwordx4 v156, s[8:11], s62 offen lds
	s_mov_b32 m0, s37
	s_nop 0
	buffer_load_dwordx4 v153, s[48:51], s64 offen lds
	s_mov_b32 m0, s38
	s_nop 0
	buffer_load_dwordx4 v155, s[48:51], s64 offen lds
	s_waitcnt vmcnt(8)
	s_waitcnt lgkmcnt(0)
	s_barrier
	s_waitcnt lgkmcnt(0)
	v_mfma_f32_16x16x32_f16 v[54:57], v[164:167], v[196:199], v[54:57]
	v_mfma_f32_16x16x32_f16 v[46:49], v[168:171], v[196:199], v[46:49]
	v_mfma_f32_16x16x32_f16 v[38:41], v[164:167], v[204:207], v[38:41]
	v_mfma_f32_16x16x32_f16 v[30:33], v[168:171], v[204:207], v[30:33]
	v_mfma_f32_16x16x32_f16 v[22:25], v[164:167], v[216:219], v[22:25]
	v_mfma_f32_16x16x32_f16 v[14:17], v[168:171], v[216:219], v[14:17]
	v_mfma_f32_16x16x32_f16 v[6:9], v[164:167], v[220:223], v[6:9]
	v_mfma_f32_16x16x32_f16 v[2:5], v[168:171], v[220:223], v[2:5]
	v_mfma_f32_16x16x32_f16 v[54:57], v[172:175], v[208:211], v[54:57]
	v_mfma_f32_16x16x32_f16 v[46:49], v[176:179], v[208:211], v[46:49]
	v_mfma_f32_16x16x32_f16 v[38:41], v[172:175], v[212:215], v[38:41]
	v_mfma_f32_16x16x32_f16 v[30:33], v[176:179], v[212:215], v[30:33]
	v_mfma_f32_16x16x32_f16 v[22:25], v[172:175], v[224:227], v[22:25]
	v_mfma_f32_16x16x32_f16 v[14:17], v[176:179], v[224:227], v[14:17]
	v_mfma_f32_16x16x32_f16 v[6:9], v[172:175], v[228:231], v[6:9]
	v_mfma_f32_16x16x32_f16 v[2:5], v[176:179], v[228:231], v[2:5]
	v_mfma_f32_16x16x32_f16 v[70:73], v[180:183], v[196:199], v[70:73]
	v_mfma_f32_16x16x32_f16 v[62:65], v[184:187], v[196:199], v[62:65]
	v_mfma_f32_16x16x32_f16 v[50:53], v[180:183], v[204:207], v[50:53]
	v_mfma_f32_16x16x32_f16 v[42:45], v[184:187], v[204:207], v[42:45]
	v_mfma_f32_16x16x32_f16 v[34:37], v[180:183], v[216:219], v[34:37]
	v_mfma_f32_16x16x32_f16 v[26:29], v[184:187], v[216:219], v[26:29]
	v_mfma_f32_16x16x32_f16 v[18:21], v[180:183], v[220:223], v[18:21]
	v_mfma_f32_16x16x32_f16 v[10:13], v[184:187], v[220:223], v[10:13]
	v_mfma_f32_16x16x32_f16 v[70:73], v[188:191], v[208:211], v[70:73]
	v_mfma_f32_16x16x32_f16 v[62:65], v[192:195], v[208:211], v[62:65]
	v_mfma_f32_16x16x32_f16 v[50:53], v[188:191], v[212:215], v[50:53]
	v_mfma_f32_16x16x32_f16 v[42:45], v[192:195], v[212:215], v[42:45]
	v_mfma_f32_16x16x32_f16 v[34:37], v[188:191], v[224:227], v[34:37]
	v_mfma_f32_16x16x32_f16 v[26:29], v[192:195], v[224:227], v[26:29]
	v_mfma_f32_16x16x32_f16 v[18:21], v[188:191], v[228:231], v[18:21]
	v_mfma_f32_16x16x32_f16 v[10:13], v[192:195], v[228:231], v[10:13]
	s_barrier

.Lc0b_final:
	s_add_i32 s55, s52, 0xfff80080
	s_and_b64 s[10:11], s[10:11], exec
	s_cselect_b32 s60, s46, s55
	s_cselect_b32 s55, s47, s53
	s_add_i32 s10, 0, 0x10000
	v_add_u32_e32 v0, s10, v157
	v_add_u32_e32 v147, s10, v158
	s_add_i32 s10, 0, 0x14000
	ds_read_b128 v[164:167], v0
	ds_read_b128 v[168:171], v0 offset:2048
	ds_read_b128 v[172:175], v147
	ds_read_b128 v[176:179], v147 offset:2048
	v_add_u32_e32 v0, s10, v157
	v_add_u32_e32 v147, s10, v158
	ds_read_b128 v[180:183], v0
	ds_read_b128 v[184:187], v0 offset:2048
	ds_read_b128 v[188:191], v147
	ds_read_b128 v[192:195], v147 offset:2048
	s_or_b32 s56, s60, 0x80
	s_or_b32 s58, s55, 0x80
	s_mov_b32 m0, s37
	ds_read_b128 v[196:199], v161
	ds_read_b128 v[204:207], v161 offset:2048
	ds_read_b128 v[208:211], v162
	ds_read_b128 v[212:215], v162 offset:2048
	ds_read_b128 v[216:219], v161 offset:4096
	ds_read_b128 v[220:223], v161 offset:6144
	ds_read_b128 v[224:227], v162 offset:4096
	ds_read_b128 v[228:231], v162 offset:6144
	buffer_load_dwordx4 v151, s[48:51], s52 offen lds
	s_mov_b32 m0, s38
	s_nop 0
	buffer_load_dwordx4 v155, s[48:51], s52 offen lds
	s_waitcnt vmcnt(16)
	s_waitcnt lgkmcnt(0)
	s_barrier
	s_waitcnt lgkmcnt(0)
	v_mfma_f32_16x16x32_f16 v[94:97], v[164:167], v[196:199], v[94:97]
	v_mfma_f32_16x16x32_f16 v[98:101], v[168:171], v[196:199], v[98:101]
	v_mfma_f32_16x16x32_f16 v[62:65], v[164:167], v[204:207], v[62:65]
	v_mfma_f32_16x16x32_f16 v[74:77], v[168:171], v[204:207], v[74:77]
	v_mfma_f32_16x16x32_f16 v[34:37], v[164:167], v[216:219], v[34:37]
	v_mfma_f32_16x16x32_f16 v[42:45], v[168:171], v[216:219], v[42:45]
	v_mfma_f32_16x16x32_f16 v[14:17], v[164:167], v[220:223], v[14:17]
	v_mfma_f32_16x16x32_f16 v[22:25], v[168:171], v[220:223], v[22:25]
	v_mfma_f32_16x16x32_f16 v[94:97], v[172:175], v[208:211], v[94:97]
	v_mfma_f32_16x16x32_f16 v[98:101], v[176:179], v[208:211], v[98:101]
	v_mfma_f32_16x16x32_f16 v[62:65], v[172:175], v[212:215], v[62:65]
	v_mfma_f32_16x16x32_f16 v[74:77], v[176:179], v[212:215], v[74:77]
	v_mfma_f32_16x16x32_f16 v[34:37], v[172:175], v[224:227], v[34:37]
	v_mfma_f32_16x16x32_f16 v[42:45], v[176:179], v[224:227], v[42:45]
	v_mfma_f32_16x16x32_f16 v[14:17], v[172:175], v[228:231], v[14:17]
	v_mfma_f32_16x16x32_f16 v[22:25], v[176:179], v[228:231], v[22:25]
	v_mfma_f32_16x16x32_f16 v[122:125], v[180:183], v[196:199], v[122:125]
	v_mfma_f32_16x16x32_f16 v[126:129], v[184:187], v[196:199], v[126:129]
	v_mfma_f32_16x16x32_f16 v[110:113], v[180:183], v[204:207], v[110:113]
	v_mfma_f32_16x16x32_f16 v[118:121], v[184:187], v[204:207], v[118:121]
	v_mfma_f32_16x16x32_f16 v[86:89], v[180:183], v[216:219], v[86:89]
	v_mfma_f32_16x16x32_f16 v[102:105], v[184:187], v[216:219], v[102:105]
	v_mfma_f32_16x16x32_f16 v[70:73], v[180:183], v[220:223], v[70:73]
	v_mfma_f32_16x16x32_f16 v[78:81], v[184:187], v[220:223], v[78:81]
	v_mfma_f32_16x16x32_f16 v[122:125], v[188:191], v[208:211], v[122:125]
	v_mfma_f32_16x16x32_f16 v[126:129], v[192:195], v[208:211], v[126:129]
	v_mfma_f32_16x16x32_f16 v[110:113], v[188:191], v[212:215], v[110:113]
	v_mfma_f32_16x16x32_f16 v[118:121], v[192:195], v[212:215], v[118:121]
	v_mfma_f32_16x16x32_f16 v[86:89], v[188:191], v[224:227], v[86:89]
	v_mfma_f32_16x16x32_f16 v[102:105], v[192:195], v[224:227], v[102:105]
	v_mfma_f32_16x16x32_f16 v[70:73], v[188:191], v[228:231], v[70:73]
	v_mfma_f32_16x16x32_f16 v[78:81], v[192:195], v[228:231], v[78:81]
	s_barrier
	s_mov_b32 s10, s50
	s_mov_b32 s11, s51
	ds_read_b128 v[196:199], v161 offset:16384
	ds_read_b128 v[204:207], v161 offset:18432
	ds_read_b128 v[208:211], v162 offset:16384
	ds_read_b128 v[212:215], v162 offset:18432
	ds_read_b128 v[216:219], v161 offset:20480
	ds_read_b128 v[220:223], v161 offset:22528
	ds_read_b128 v[224:227], v162 offset:20480
	ds_read_b128 v[228:231], v162 offset:22528
	s_add_i32 s61, s55, 0x80000
	s_waitcnt vmcnt(10)
	s_waitcnt lgkmcnt(0)
	s_barrier
	s_waitcnt lgkmcnt(0)
	v_mfma_f32_16x16x32_f16 v[54:57], v[164:167], v[196:199], v[54:57]
	v_mfma_f32_16x16x32_f16 v[66:69], v[168:171], v[196:199], v[66:69]
	v_mfma_f32_16x16x32_f16 v[30:33], v[164:167], v[204:207], v[30:33]
	v_mfma_f32_16x16x32_f16 v[38:41], v[168:171], v[204:207], v[38:41]
	v_mfma_f32_16x16x32_f16 v[10:13], v[164:167], v[216:219], v[10:13]
	v_mfma_f32_16x16x32_f16 v[18:21], v[168:171], v[216:219], v[18:21]
	v_mfma_f32_16x16x32_f16 v[2:5], v[164:167], v[220:223], v[2:5]
	v_mfma_f32_16x16x32_f16 v[6:9], v[168:171], v[220:223], v[6:9]
	v_mfma_f32_16x16x32_f16 v[54:57], v[172:175], v[208:211], v[54:57]
	v_mfma_f32_16x16x32_f16 v[66:69], v[176:179], v[208:211], v[66:69]
	v_mfma_f32_16x16x32_f16 v[30:33], v[172:175], v[212:215], v[30:33]
	v_mfma_f32_16x16x32_f16 v[38:41], v[176:179], v[212:215], v[38:41]
	v_mfma_f32_16x16x32_f16 v[10:13], v[172:175], v[224:227], v[10:13]
	v_mfma_f32_16x16x32_f16 v[18:21], v[176:179], v[224:227], v[18:21]
	v_mfma_f32_16x16x32_f16 v[2:5], v[172:175], v[228:231], v[2:5]
	v_mfma_f32_16x16x32_f16 v[6:9], v[176:179], v[228:231], v[6:9]
	v_mfma_f32_16x16x32_f16 v[106:109], v[180:183], v[196:199], v[106:109]
	v_mfma_f32_16x16x32_f16 v[114:117], v[184:187], v[196:199], v[114:117]
	v_mfma_f32_16x16x32_f16 v[82:85], v[180:183], v[204:207], v[82:85]
	v_mfma_f32_16x16x32_f16 v[90:93], v[184:187], v[204:207], v[90:93]
	v_mfma_f32_16x16x32_f16 v[46:49], v[180:183], v[216:219], v[46:49]
	v_mfma_f32_16x16x32_f16 v[58:61], v[184:187], v[216:219], v[58:61]
	v_mfma_f32_16x16x32_f16 v[26:29], v[180:183], v[220:223], v[26:29]
	v_mfma_f32_16x16x32_f16 v[50:53], v[184:187], v[220:223], v[50:53]
	v_mfma_f32_16x16x32_f16 v[106:109], v[188:191], v[208:211], v[106:109]
	v_mfma_f32_16x16x32_f16 v[114:117], v[192:195], v[208:211], v[114:117]
	v_mfma_f32_16x16x32_f16 v[82:85], v[188:191], v[212:215], v[82:85]
	v_mfma_f32_16x16x32_f16 v[90:93], v[192:195], v[212:215], v[90:93]
	v_mfma_f32_16x16x32_f16 v[46:49], v[188:191], v[224:227], v[46:49]
	v_mfma_f32_16x16x32_f16 v[58:61], v[192:195], v[224:227], v[58:61]
	v_mfma_f32_16x16x32_f16 v[26:29], v[188:191], v[228:231], v[26:29]
	v_mfma_f32_16x16x32_f16 v[50:53], v[192:195], v[228:231], v[50:53]
	s_barrier
	s_add_i32 s61, 0, 0x18000
	v_add_u32_e32 v0, s61, v157
	v_add_u32_e32 v147, s61, v158
	s_add_i32 s61, 0, 0x1c000
	ds_read_b128 v[164:167], v0
	ds_read_b128 v[168:171], v0 offset:2048
	ds_read_b128 v[172:175], v147
	ds_read_b128 v[176:179], v147 offset:2048
	v_add_u32_e32 v0, s61, v157
	v_add_u32_e32 v147, s61, v158
	ds_read_b128 v[180:183], v0
	ds_read_b128 v[184:187], v0 offset:2048
	ds_read_b128 v[188:191], v147
	ds_read_b128 v[192:195], v147 offset:2048
	s_add_i32 s60, s60, 0x80000
	ds_read_b128 v[196:199], v161 offset:32768
	ds_read_b128 v[204:207], v161 offset:34816
	ds_read_b128 v[208:211], v162 offset:32768
	ds_read_b128 v[212:215], v162 offset:34816
	ds_read_b128 v[216:219], v161 offset:36864
	ds_read_b128 v[220:223], v161 offset:38912
	ds_read_b128 v[224:227], v162 offset:36864
	ds_read_b128 v[228:231], v162 offset:38912
	s_waitcnt vmcnt(0)
	s_waitcnt lgkmcnt(0)
	s_barrier
	s_waitcnt lgkmcnt(0)
	v_mfma_f32_16x16x32_f16 v[94:97], v[164:167], v[196:199], v[94:97]
	v_mfma_f32_16x16x32_f16 v[98:101], v[168:171], v[196:199], v[98:101]
	v_mfma_f32_16x16x32_f16 v[62:65], v[164:167], v[204:207], v[62:65]
	v_mfma_f32_16x16x32_f16 v[74:77], v[168:171], v[204:207], v[74:77]
	v_mfma_f32_16x16x32_f16 v[34:37], v[164:167], v[216:219], v[34:37]
	v_mfma_f32_16x16x32_f16 v[42:45], v[168:171], v[216:219], v[42:45]
	v_mfma_f32_16x16x32_f16 v[14:17], v[164:167], v[220:223], v[14:17]
	v_mfma_f32_16x16x32_f16 v[22:25], v[168:171], v[220:223], v[22:25]
	v_mfma_f32_16x16x32_f16 v[94:97], v[172:175], v[208:211], v[94:97]
	v_mfma_f32_16x16x32_f16 v[98:101], v[176:179], v[208:211], v[98:101]
	v_mfma_f32_16x16x32_f16 v[62:65], v[172:175], v[212:215], v[62:65]
	v_mfma_f32_16x16x32_f16 v[74:77], v[176:179], v[212:215], v[74:77]
	v_mfma_f32_16x16x32_f16 v[34:37], v[172:175], v[224:227], v[34:37]
	v_mfma_f32_16x16x32_f16 v[42:45], v[176:179], v[224:227], v[42:45]
	v_mfma_f32_16x16x32_f16 v[14:17], v[172:175], v[228:231], v[14:17]
	v_mfma_f32_16x16x32_f16 v[22:25], v[176:179], v[228:231], v[22:25]
	v_mfma_f32_16x16x32_f16 v[122:125], v[180:183], v[196:199], v[122:125]
	v_mfma_f32_16x16x32_f16 v[126:129], v[184:187], v[196:199], v[126:129]
	v_mfma_f32_16x16x32_f16 v[110:113], v[180:183], v[204:207], v[110:113]
	v_mfma_f32_16x16x32_f16 v[118:121], v[184:187], v[204:207], v[118:121]
	v_mfma_f32_16x16x32_f16 v[86:89], v[180:183], v[216:219], v[86:89]
	v_mfma_f32_16x16x32_f16 v[102:105], v[184:187], v[216:219], v[102:105]
	v_mfma_f32_16x16x32_f16 v[70:73], v[180:183], v[220:223], v[70:73]
	v_mfma_f32_16x16x32_f16 v[78:81], v[184:187], v[220:223], v[78:81]
	v_mfma_f32_16x16x32_f16 v[122:125], v[188:191], v[208:211], v[122:125]
	v_mfma_f32_16x16x32_f16 v[126:129], v[192:195], v[208:211], v[126:129]
	v_mfma_f32_16x16x32_f16 v[110:113], v[188:191], v[212:215], v[110:113]
	v_mfma_f32_16x16x32_f16 v[118:121], v[192:195], v[212:215], v[118:121]
	v_mfma_f32_16x16x32_f16 v[86:89], v[188:191], v[224:227], v[86:89]
	v_mfma_f32_16x16x32_f16 v[102:105], v[192:195], v[224:227], v[102:105]
	v_mfma_f32_16x16x32_f16 v[70:73], v[188:191], v[228:231], v[70:73]
	v_mfma_f32_16x16x32_f16 v[78:81], v[192:195], v[228:231], v[78:81]
	s_barrier
	ds_read_b128 v[196:199], v161 offset:49152
	ds_read_b128 v[204:207], v161 offset:51200
	ds_read_b128 v[208:211], v162 offset:49152
	ds_read_b128 v[212:215], v162 offset:51200
	ds_read_b128 v[216:219], v161 offset:53248
	ds_read_b128 v[220:223], v161 offset:55296
	ds_read_b128 v[224:227], v162 offset:53248
	ds_read_b128 v[228:231], v162 offset:55296
	s_add_i32 s55, s55, 0x80080
	s_waitcnt vmcnt(0)
	s_waitcnt lgkmcnt(0)
	s_barrier
	s_waitcnt lgkmcnt(0)
	v_mfma_f32_16x16x32_f16 v[54:57], v[164:167], v[196:199], v[54:57]
	v_mfma_f32_16x16x32_f16 v[66:69], v[168:171], v[196:199], v[66:69]
	v_mfma_f32_16x16x32_f16 v[30:33], v[164:167], v[204:207], v[30:33]
	v_mfma_f32_16x16x32_f16 v[38:41], v[168:171], v[204:207], v[38:41]
	v_mfma_f32_16x16x32_f16 v[10:13], v[164:167], v[216:219], v[10:13]
	v_mfma_f32_16x16x32_f16 v[18:21], v[168:171], v[216:219], v[18:21]
	v_mfma_f32_16x16x32_f16 v[2:5], v[164:167], v[220:223], v[2:5]
	v_mfma_f32_16x16x32_f16 v[6:9], v[168:171], v[220:223], v[6:9]
	v_mfma_f32_16x16x32_f16 v[54:57], v[172:175], v[208:211], v[54:57]
	v_mfma_f32_16x16x32_f16 v[66:69], v[176:179], v[208:211], v[66:69]
	v_mfma_f32_16x16x32_f16 v[30:33], v[172:175], v[212:215], v[30:33]
	v_mfma_f32_16x16x32_f16 v[38:41], v[176:179], v[212:215], v[38:41]
	v_mfma_f32_16x16x32_f16 v[10:13], v[172:175], v[224:227], v[10:13]
	v_mfma_f32_16x16x32_f16 v[18:21], v[176:179], v[224:227], v[18:21]
	v_mfma_f32_16x16x32_f16 v[2:5], v[172:175], v[228:231], v[2:5]
	v_mfma_f32_16x16x32_f16 v[6:9], v[176:179], v[228:231], v[6:9]
	v_mfma_f32_16x16x32_f16 v[106:109], v[180:183], v[196:199], v[106:109]
	v_mfma_f32_16x16x32_f16 v[114:117], v[184:187], v[196:199], v[114:117]
	v_mfma_f32_16x16x32_f16 v[82:85], v[180:183], v[204:207], v[82:85]
	v_mfma_f32_16x16x32_f16 v[90:93], v[184:187], v[204:207], v[90:93]
	v_mfma_f32_16x16x32_f16 v[46:49], v[180:183], v[216:219], v[46:49]
	v_mfma_f32_16x16x32_f16 v[58:61], v[184:187], v[216:219], v[58:61]
	v_mfma_f32_16x16x32_f16 v[26:29], v[180:183], v[220:223], v[26:29]
	v_mfma_f32_16x16x32_f16 v[50:53], v[184:187], v[220:223], v[50:53]
	v_mfma_f32_16x16x32_f16 v[106:109], v[188:191], v[208:211], v[106:109]
	v_mfma_f32_16x16x32_f16 v[114:117], v[192:195], v[208:211], v[114:117]
	v_mfma_f32_16x16x32_f16 v[82:85], v[188:191], v[212:215], v[82:85]
	v_mfma_f32_16x16x32_f16 v[90:93], v[192:195], v[212:215], v[90:93]
	v_mfma_f32_16x16x32_f16 v[46:49], v[188:191], v[224:227], v[46:49]
	v_mfma_f32_16x16x32_f16 v[58:61], v[192:195], v[224:227], v[58:61]
	v_mfma_f32_16x16x32_f16 v[26:29], v[188:191], v[228:231], v[26:29]
	v_mfma_f32_16x16x32_f16 v[50:53], v[192:195], v[228:231], v[50:53]
	s_barrier
	s_branch .Lc0b_tail
.Lc0b_last:
	s_add_i32 s55, s52, 0xfff80080
	s_and_b64 s[10:11], s[10:11], exec
	s_cselect_b32 s60, s46, s55
	s_cselect_b32 s55, s47, s53
	s_add_i32 s10, 0, 0x10000
	v_add_u32_e32 v0, s10, v157
	v_add_u32_e32 v147, s10, v158
	s_add_i32 s10, 0, 0x14000
	ds_read_b128 v[164:167], v0
	ds_read_b128 v[168:171], v0 offset:2048
	ds_read_b128 v[172:175], v147
	ds_read_b128 v[176:179], v147 offset:2048
	v_add_u32_e32 v0, s10, v157
	v_add_u32_e32 v147, s10, v158
	ds_read_b128 v[180:183], v0
	ds_read_b128 v[184:187], v0 offset:2048
	ds_read_b128 v[188:191], v147
	ds_read_b128 v[192:195], v147 offset:2048
	s_or_b32 s56, s60, 0x80
	s_or_b32 s58, s55, 0x80
	s_mov_b32 m0, s37
	ds_read_b128 v[196:199], v161
	ds_read_b128 v[204:207], v161 offset:2048
	ds_read_b128 v[208:211], v162
	ds_read_b128 v[212:215], v162 offset:2048
	ds_read_b128 v[216:219], v161 offset:4096
	ds_read_b128 v[220:223], v161 offset:6144
	ds_read_b128 v[224:227], v162 offset:4096
	ds_read_b128 v[228:231], v162 offset:6144
	buffer_load_dwordx4 v151, s[48:51], s52 offen lds
	s_mov_b32 m0, s38
	s_nop 0
	buffer_load_dwordx4 v155, s[48:51], s52 offen lds
	s_waitcnt vmcnt(16)
	s_waitcnt lgkmcnt(0)
	s_barrier
	s_waitcnt lgkmcnt(0)
	v_mfma_f32_16x16x32_f16 v[94:97], v[164:167], v[196:199], v[94:97]
	v_mfma_f32_16x16x32_f16 v[98:101], v[168:171], v[196:199], v[98:101]
	v_mfma_f32_16x16x32_f16 v[62:65], v[164:167], v[204:207], v[62:65]
	v_mfma_f32_16x16x32_f16 v[74:77], v[168:171], v[204:207], v[74:77]
	v_mfma_f32_16x16x32_f16 v[34:37], v[164:167], v[216:219], v[34:37]
	v_mfma_f32_16x16x32_f16 v[42:45], v[168:171], v[216:219], v[42:45]
	v_mfma_f32_16x16x32_f16 v[14:17], v[164:167], v[220:223], v[14:17]
	v_mfma_f32_16x16x32_f16 v[22:25], v[168:171], v[220:223], v[22:25]
	v_mfma_f32_16x16x32_f16 v[94:97], v[172:175], v[208:211], v[94:97]
	v_mfma_f32_16x16x32_f16 v[98:101], v[176:179], v[208:211], v[98:101]
	v_mfma_f32_16x16x32_f16 v[62:65], v[172:175], v[212:215], v[62:65]
	v_mfma_f32_16x16x32_f16 v[74:77], v[176:179], v[212:215], v[74:77]
	v_mfma_f32_16x16x32_f16 v[34:37], v[172:175], v[224:227], v[34:37]
	v_mfma_f32_16x16x32_f16 v[42:45], v[176:179], v[224:227], v[42:45]
	v_mfma_f32_16x16x32_f16 v[14:17], v[172:175], v[228:231], v[14:17]
	v_mfma_f32_16x16x32_f16 v[22:25], v[176:179], v[228:231], v[22:25]
	v_mfma_f32_16x16x32_f16 v[122:125], v[180:183], v[196:199], v[122:125]
	v_mfma_f32_16x16x32_f16 v[126:129], v[184:187], v[196:199], v[126:129]
	v_mfma_f32_16x16x32_f16 v[110:113], v[180:183], v[204:207], v[110:113]
	v_mfma_f32_16x16x32_f16 v[118:121], v[184:187], v[204:207], v[118:121]
	v_mfma_f32_16x16x32_f16 v[86:89], v[180:183], v[216:219], v[86:89]
	v_mfma_f32_16x16x32_f16 v[102:105], v[184:187], v[216:219], v[102:105]
	v_mfma_f32_16x16x32_f16 v[70:73], v[180:183], v[220:223], v[70:73]
	v_mfma_f32_16x16x32_f16 v[78:81], v[184:187], v[220:223], v[78:81]
	v_mfma_f32_16x16x32_f16 v[122:125], v[188:191], v[208:211], v[122:125]
	v_mfma_f32_16x16x32_f16 v[126:129], v[192:195], v[208:211], v[126:129]
	v_mfma_f32_16x16x32_f16 v[110:113], v[188:191], v[212:215], v[110:113]
	v_mfma_f32_16x16x32_f16 v[118:121], v[192:195], v[212:215], v[118:121]
	v_mfma_f32_16x16x32_f16 v[86:89], v[188:191], v[224:227], v[86:89]
	v_mfma_f32_16x16x32_f16 v[102:105], v[192:195], v[224:227], v[102:105]
	v_mfma_f32_16x16x32_f16 v[70:73], v[188:191], v[228:231], v[70:73]
	v_mfma_f32_16x16x32_f16 v[78:81], v[192:195], v[228:231], v[78:81]
	s_barrier
	s_mov_b32 m0, s2
	s_mov_b32 s10, s50
	s_mov_b32 s11, s51
	ds_read_b128 v[196:199], v161 offset:16384
	ds_read_b128 v[204:207], v161 offset:18432
	ds_read_b128 v[208:211], v162 offset:16384
	ds_read_b128 v[212:215], v162 offset:18432
	ds_read_b128 v[216:219], v161 offset:20480
	ds_read_b128 v[220:223], v161 offset:22528
	ds_read_b128 v[224:227], v162 offset:20480
	ds_read_b128 v[228:231], v162 offset:22528
	buffer_load_dwordx4 v153, s[8:11], s55 offen lds
	s_mov_b32 m0, s3
	s_add_i32 s61, s55, 0x80000
	buffer_load_dwordx4 v156, s[8:11], s55 offen lds
	s_mov_b32 m0, s20
	s_nop 0
	buffer_load_dwordx4 v153, s[8:11], s61 offen lds
	s_mov_b32 m0, s21
	s_nop 0
	buffer_load_dwordx4 v156, s[8:11], s61 offen lds
	s_mov_b32 m0, s1
	s_nop 0
	buffer_load_dwordx4 v151, s[48:51], s60 offen lds
	s_mov_b32 m0, s26
	s_nop 0
	buffer_load_dwordx4 v155, s[48:51], s60 offen lds
	s_waitcnt vmcnt(16)
	s_waitcnt lgkmcnt(0)
	s_barrier
	s_waitcnt lgkmcnt(0)
	v_mfma_f32_16x16x32_f16 v[54:57], v[164:167], v[196:199], v[54:57]
	v_mfma_f32_16x16x32_f16 v[66:69], v[168:171], v[196:199], v[66:69]
	v_mfma_f32_16x16x32_f16 v[30:33], v[164:167], v[204:207], v[30:33]
	v_mfma_f32_16x16x32_f16 v[38:41], v[168:171], v[204:207], v[38:41]
	v_mfma_f32_16x16x32_f16 v[10:13], v[164:167], v[216:219], v[10:13]
	v_mfma_f32_16x16x32_f16 v[18:21], v[168:171], v[216:219], v[18:21]
	v_mfma_f32_16x16x32_f16 v[2:5], v[164:167], v[220:223], v[2:5]
	v_mfma_f32_16x16x32_f16 v[6:9], v[168:171], v[220:223], v[6:9]
	v_mfma_f32_16x16x32_f16 v[54:57], v[172:175], v[208:211], v[54:57]
	v_mfma_f32_16x16x32_f16 v[66:69], v[176:179], v[208:211], v[66:69]
	v_mfma_f32_16x16x32_f16 v[30:33], v[172:175], v[212:215], v[30:33]
	v_mfma_f32_16x16x32_f16 v[38:41], v[176:179], v[212:215], v[38:41]
	v_mfma_f32_16x16x32_f16 v[10:13], v[172:175], v[224:227], v[10:13]
	v_mfma_f32_16x16x32_f16 v[18:21], v[176:179], v[224:227], v[18:21]
	v_mfma_f32_16x16x32_f16 v[2:5], v[172:175], v[228:231], v[2:5]
	v_mfma_f32_16x16x32_f16 v[6:9], v[176:179], v[228:231], v[6:9]
	v_mfma_f32_16x16x32_f16 v[106:109], v[180:183], v[196:199], v[106:109]
	v_mfma_f32_16x16x32_f16 v[114:117], v[184:187], v[196:199], v[114:117]
	v_mfma_f32_16x16x32_f16 v[82:85], v[180:183], v[204:207], v[82:85]
	v_mfma_f32_16x16x32_f16 v[90:93], v[184:187], v[204:207], v[90:93]
	v_mfma_f32_16x16x32_f16 v[46:49], v[180:183], v[216:219], v[46:49]
	v_mfma_f32_16x16x32_f16 v[58:61], v[184:187], v[216:219], v[58:61]
	v_mfma_f32_16x16x32_f16 v[26:29], v[180:183], v[220:223], v[26:29]
	v_mfma_f32_16x16x32_f16 v[50:53], v[184:187], v[220:223], v[50:53]
	v_mfma_f32_16x16x32_f16 v[106:109], v[188:191], v[208:211], v[106:109]
	v_mfma_f32_16x16x32_f16 v[114:117], v[192:195], v[208:211], v[114:117]
	v_mfma_f32_16x16x32_f16 v[82:85], v[188:191], v[212:215], v[82:85]
	v_mfma_f32_16x16x32_f16 v[90:93], v[192:195], v[212:215], v[90:93]
	v_mfma_f32_16x16x32_f16 v[46:49], v[188:191], v[224:227], v[46:49]
	v_mfma_f32_16x16x32_f16 v[58:61], v[192:195], v[224:227], v[58:61]
	v_mfma_f32_16x16x32_f16 v[26:29], v[188:191], v[228:231], v[26:29]
	v_mfma_f32_16x16x32_f16 v[50:53], v[192:195], v[228:231], v[50:53]
	s_barrier
	s_add_i32 s61, 0, 0x18000
	v_add_u32_e32 v0, s61, v157
	v_add_u32_e32 v147, s61, v158
	s_add_i32 s61, 0, 0x1c000
	ds_read_b128 v[164:167], v0
	ds_read_b128 v[168:171], v0 offset:2048
	ds_read_b128 v[172:175], v147
	ds_read_b128 v[176:179], v147 offset:2048
	v_add_u32_e32 v0, s61, v157
	v_add_u32_e32 v147, s61, v158
	ds_read_b128 v[180:183], v0
	ds_read_b128 v[184:187], v0 offset:2048
	ds_read_b128 v[188:191], v147
	ds_read_b128 v[192:195], v147 offset:2048
	s_add_i32 s60, s60, 0x80000
	s_mov_b32 m0, s27
	ds_read_b128 v[196:199], v161 offset:32768
	ds_read_b128 v[204:207], v161 offset:34816
	ds_read_b128 v[208:211], v162 offset:32768
	ds_read_b128 v[212:215], v162 offset:34816
	ds_read_b128 v[216:219], v161 offset:36864
	ds_read_b128 v[220:223], v161 offset:38912
	ds_read_b128 v[224:227], v162 offset:36864
	ds_read_b128 v[228:231], v162 offset:38912
	buffer_load_dwordx4 v151, s[48:51], s60 offen lds
	s_mov_b32 m0, s28
	s_nop 0
	buffer_load_dwordx4 v155, s[48:51], s60 offen lds
	s_waitcnt vmcnt(8)
	s_waitcnt lgkmcnt(0)
	s_barrier
	s_waitcnt lgkmcnt(0)
	v_mfma_f32_16x16x32_f16 v[94:97], v[164:167], v[196:199], v[94:97]
	v_mfma_f32_16x16x32_f16 v[98:101], v[168:171], v[196:199], v[98:101]
	v_mfma_f32_16x16x32_f16 v[62:65], v[164:167], v[204:207], v[62:65]
	v_mfma_f32_16x16x32_f16 v[74:77], v[168:171], v[204:207], v[74:77]
	v_mfma_f32_16x16x32_f16 v[34:37], v[164:167], v[216:219], v[34:37]
	v_mfma_f32_16x16x32_f16 v[42:45], v[168:171], v[216:219], v[42:45]
	v_mfma_f32_16x16x32_f16 v[14:17], v[164:167], v[220:223], v[14:17]
	v_mfma_f32_16x16x32_f16 v[22:25], v[168:171], v[220:223], v[22:25]
	v_mfma_f32_16x16x32_f16 v[94:97], v[172:175], v[208:211], v[94:97]
	v_mfma_f32_16x16x32_f16 v[98:101], v[176:179], v[208:211], v[98:101]
	v_mfma_f32_16x16x32_f16 v[62:65], v[172:175], v[212:215], v[62:65]
	v_mfma_f32_16x16x32_f16 v[74:77], v[176:179], v[212:215], v[74:77]
	v_mfma_f32_16x16x32_f16 v[34:37], v[172:175], v[224:227], v[34:37]
	v_mfma_f32_16x16x32_f16 v[42:45], v[176:179], v[224:227], v[42:45]
	v_mfma_f32_16x16x32_f16 v[14:17], v[172:175], v[228:231], v[14:17]
	v_mfma_f32_16x16x32_f16 v[22:25], v[176:179], v[228:231], v[22:25]
	v_mfma_f32_16x16x32_f16 v[122:125], v[180:183], v[196:199], v[122:125]
	v_mfma_f32_16x16x32_f16 v[126:129], v[184:187], v[196:199], v[126:129]
	v_mfma_f32_16x16x32_f16 v[110:113], v[180:183], v[204:207], v[110:113]
	v_mfma_f32_16x16x32_f16 v[118:121], v[184:187], v[204:207], v[118:121]
	v_mfma_f32_16x16x32_f16 v[86:89], v[180:183], v[216:219], v[86:89]
	v_mfma_f32_16x16x32_f16 v[102:105], v[184:187], v[216:219], v[102:105]
	v_mfma_f32_16x16x32_f16 v[70:73], v[180:183], v[220:223], v[70:73]
	v_mfma_f32_16x16x32_f16 v[78:81], v[184:187], v[220:223], v[78:81]
	v_mfma_f32_16x16x32_f16 v[122:125], v[188:191], v[208:211], v[122:125]
	v_mfma_f32_16x16x32_f16 v[126:129], v[192:195], v[208:211], v[126:129]
	v_mfma_f32_16x16x32_f16 v[110:113], v[188:191], v[212:215], v[110:113]
	v_mfma_f32_16x16x32_f16 v[118:121], v[192:195], v[212:215], v[118:121]
	v_mfma_f32_16x16x32_f16 v[86:89], v[188:191], v[224:227], v[86:89]
	v_mfma_f32_16x16x32_f16 v[102:105], v[192:195], v[224:227], v[102:105]
	v_mfma_f32_16x16x32_f16 v[70:73], v[188:191], v[228:231], v[70:73]
	v_mfma_f32_16x16x32_f16 v[78:81], v[192:195], v[228:231], v[78:81]
	s_barrier
	s_mov_b32 m0, s29
	ds_read_b128 v[196:199], v161 offset:49152
	ds_read_b128 v[204:207], v161 offset:51200
	ds_read_b128 v[208:211], v162 offset:49152
	ds_read_b128 v[212:215], v162 offset:51200
	ds_read_b128 v[216:219], v161 offset:53248
	ds_read_b128 v[220:223], v161 offset:55296
	ds_read_b128 v[224:227], v162 offset:53248
	ds_read_b128 v[228:231], v162 offset:55296
	buffer_load_dwordx4 v153, s[8:11], s58 offen lds
	s_mov_b32 m0, s30
	s_add_i32 s55, s55, 0x80080
	buffer_load_dwordx4 v156, s[8:11], s58 offen lds
	s_mov_b32 m0, s35
	s_nop 0
	buffer_load_dwordx4 v153, s[8:11], s55 offen lds
	s_mov_b32 m0, s36
	s_nop 0
	buffer_load_dwordx4 v156, s[8:11], s55 offen lds
	s_mov_b32 m0, s31
	s_nop 0
	buffer_load_dwordx4 v151, s[48:51], s56 offen lds
	s_mov_b32 m0, s34
	s_nop 0
	buffer_load_dwordx4 v155, s[48:51], s56 offen lds
	s_waitcnt vmcnt(8)
	s_waitcnt lgkmcnt(0)
	s_barrier
	s_waitcnt lgkmcnt(0)
	v_mfma_f32_16x16x32_f16 v[54:57], v[164:167], v[196:199], v[54:57]
	v_mfma_f32_16x16x32_f16 v[66:69], v[168:171], v[196:199], v[66:69]
	v_mfma_f32_16x16x32_f16 v[30:33], v[164:167], v[204:207], v[30:33]
	v_mfma_f32_16x16x32_f16 v[38:41], v[168:171], v[204:207], v[38:41]
	v_mfma_f32_16x16x32_f16 v[10:13], v[164:167], v[216:219], v[10:13]
	v_mfma_f32_16x16x32_f16 v[18:21], v[168:171], v[216:219], v[18:21]
	v_mfma_f32_16x16x32_f16 v[2:5], v[164:167], v[220:223], v[2:5]
	v_mfma_f32_16x16x32_f16 v[6:9], v[168:171], v[220:223], v[6:9]
	v_mfma_f32_16x16x32_f16 v[54:57], v[172:175], v[208:211], v[54:57]
	v_mfma_f32_16x16x32_f16 v[66:69], v[176:179], v[208:211], v[66:69]
	v_mfma_f32_16x16x32_f16 v[30:33], v[172:175], v[212:215], v[30:33]
	v_mfma_f32_16x16x32_f16 v[38:41], v[176:179], v[212:215], v[38:41]
	v_mfma_f32_16x16x32_f16 v[10:13], v[172:175], v[224:227], v[10:13]
	v_mfma_f32_16x16x32_f16 v[18:21], v[176:179], v[224:227], v[18:21]
	v_mfma_f32_16x16x32_f16 v[2:5], v[172:175], v[228:231], v[2:5]
	v_mfma_f32_16x16x32_f16 v[6:9], v[176:179], v[228:231], v[6:9]
	v_mfma_f32_16x16x32_f16 v[106:109], v[180:183], v[196:199], v[106:109]
	v_mfma_f32_16x16x32_f16 v[114:117], v[184:187], v[196:199], v[114:117]
	v_mfma_f32_16x16x32_f16 v[82:85], v[180:183], v[204:207], v[82:85]
	v_mfma_f32_16x16x32_f16 v[90:93], v[184:187], v[204:207], v[90:93]
	v_mfma_f32_16x16x32_f16 v[46:49], v[180:183], v[216:219], v[46:49]
	v_mfma_f32_16x16x32_f16 v[58:61], v[184:187], v[216:219], v[58:61]
	v_mfma_f32_16x16x32_f16 v[26:29], v[180:183], v[220:223], v[26:29]
	v_mfma_f32_16x16x32_f16 v[50:53], v[184:187], v[220:223], v[50:53]
	v_mfma_f32_16x16x32_f16 v[106:109], v[188:191], v[208:211], v[106:109]
	v_mfma_f32_16x16x32_f16 v[114:117], v[192:195], v[208:211], v[114:117]
	v_mfma_f32_16x16x32_f16 v[82:85], v[188:191], v[212:215], v[82:85]
	v_mfma_f32_16x16x32_f16 v[90:93], v[192:195], v[212:215], v[90:93]
	v_mfma_f32_16x16x32_f16 v[46:49], v[188:191], v[224:227], v[46:49]
	v_mfma_f32_16x16x32_f16 v[58:61], v[192:195], v[224:227], v[58:61]
	v_mfma_f32_16x16x32_f16 v[26:29], v[188:191], v[228:231], v[26:29]
	v_mfma_f32_16x16x32_f16 v[50:53], v[192:195], v[228:231], v[50:53]
	s_barrier
	s_branch .Lc0b_tail
.LBB0_162:
	s_cmp_eq_u32 s54, -2
	s_cbranch_scc1 .Lc0b_first
	s_cmp_eq_u32 s54, 28
	s_cbranch_scc0 .Lc0b_norm
	s_cmp_eq_u64 s[4:5], 0
	s_cbranch_scc1 .Lc0b_final
	s_branch .Lc0b_last
.Lc0b_norm:
	s_add_i32 s55, s52, 0xfff80080
	s_and_b64 s[10:11], s[10:11], exec
	s_cselect_b32 s60, s46, s55
	s_cselect_b32 s55, s47, s53
	s_add_i32 s10, 0, 0x10000
	v_add_u32_e32 v0, s10, v157
	v_add_u32_e32 v147, s10, v158
	s_add_i32 s10, 0, 0x14000
	ds_read_b128 v[164:167], v0
	ds_read_b128 v[168:171], v0 offset:2048
	ds_read_b128 v[172:175], v147
	ds_read_b128 v[176:179], v147 offset:2048
	v_add_u32_e32 v0, s10, v157
	v_add_u32_e32 v147, s10, v158
	ds_read_b128 v[180:183], v0
	ds_read_b128 v[184:187], v0 offset:2048
	ds_read_b128 v[188:191], v147
	ds_read_b128 v[192:195], v147 offset:2048
	s_or_b32 s56, s60, 0x80
	s_or_b32 s58, s55, 0x80
	s_mov_b32 m0, s37
	ds_read_b128 v[196:199], v161
	ds_read_b128 v[204:207], v161 offset:2048
	ds_read_b128 v[208:211], v162
	ds_read_b128 v[212:215], v162 offset:2048
	ds_read_b128 v[216:219], v161 offset:4096
	ds_read_b128 v[220:223], v161 offset:6144
	ds_read_b128 v[224:227], v162 offset:4096
	ds_read_b128 v[228:231], v162 offset:6144
	buffer_load_dwordx4 v151, s[48:51], s52 offen lds
	s_mov_b32 m0, s38
	s_nop 0
	buffer_load_dwordx4 v155, s[48:51], s52 offen lds
	s_waitcnt vmcnt(8)
	s_waitcnt lgkmcnt(0)
	s_barrier
	s_waitcnt lgkmcnt(0)
	v_mfma_f32_16x16x32_f16 v[94:97], v[164:167], v[196:199], v[94:97]
	v_mfma_f32_16x16x32_f16 v[98:101], v[168:171], v[196:199], v[98:101]
	v_mfma_f32_16x16x32_f16 v[62:65], v[164:167], v[204:207], v[62:65]
	v_mfma_f32_16x16x32_f16 v[74:77], v[168:171], v[204:207], v[74:77]
	v_mfma_f32_16x16x32_f16 v[34:37], v[164:167], v[216:219], v[34:37]
	v_mfma_f32_16x16x32_f16 v[42:45], v[168:171], v[216:219], v[42:45]
	v_mfma_f32_16x16x32_f16 v[14:17], v[164:167], v[220:223], v[14:17]
	v_mfma_f32_16x16x32_f16 v[22:25], v[168:171], v[220:223], v[22:25]
	v_mfma_f32_16x16x32_f16 v[94:97], v[172:175], v[208:211], v[94:97]
	v_mfma_f32_16x16x32_f16 v[98:101], v[176:179], v[208:211], v[98:101]
	v_mfma_f32_16x16x32_f16 v[62:65], v[172:175], v[212:215], v[62:65]
	v_mfma_f32_16x16x32_f16 v[74:77], v[176:179], v[212:215], v[74:77]
	v_mfma_f32_16x16x32_f16 v[34:37], v[172:175], v[224:227], v[34:37]
	v_mfma_f32_16x16x32_f16 v[42:45], v[176:179], v[224:227], v[42:45]
	v_mfma_f32_16x16x32_f16 v[14:17], v[172:175], v[228:231], v[14:17]
	v_mfma_f32_16x16x32_f16 v[22:25], v[176:179], v[228:231], v[22:25]
	v_mfma_f32_16x16x32_f16 v[122:125], v[180:183], v[196:199], v[122:125]
	v_mfma_f32_16x16x32_f16 v[126:129], v[184:187], v[196:199], v[126:129]
	v_mfma_f32_16x16x32_f16 v[110:113], v[180:183], v[204:207], v[110:113]
	v_mfma_f32_16x16x32_f16 v[118:121], v[184:187], v[204:207], v[118:121]
	v_mfma_f32_16x16x32_f16 v[86:89], v[180:183], v[216:219], v[86:89]
	v_mfma_f32_16x16x32_f16 v[102:105], v[184:187], v[216:219], v[102:105]
	v_mfma_f32_16x16x32_f16 v[70:73], v[180:183], v[220:223], v[70:73]
	v_mfma_f32_16x16x32_f16 v[78:81], v[184:187], v[220:223], v[78:81]
	v_mfma_f32_16x16x32_f16 v[122:125], v[188:191], v[208:211], v[122:125]
	v_mfma_f32_16x16x32_f16 v[126:129], v[192:195], v[208:211], v[126:129]
	v_mfma_f32_16x16x32_f16 v[110:113], v[188:191], v[212:215], v[110:113]
	v_mfma_f32_16x16x32_f16 v[118:121], v[192:195], v[212:215], v[118:121]
	v_mfma_f32_16x16x32_f16 v[86:89], v[188:191], v[224:227], v[86:89]
	v_mfma_f32_16x16x32_f16 v[102:105], v[192:195], v[224:227], v[102:105]
	v_mfma_f32_16x16x32_f16 v[70:73], v[188:191], v[228:231], v[70:73]
	v_mfma_f32_16x16x32_f16 v[78:81], v[192:195], v[228:231], v[78:81]
	s_barrier
	s_mov_b32 m0, s2
	s_mov_b32 s10, s50
	s_mov_b32 s11, s51
	ds_read_b128 v[196:199], v161 offset:16384
	ds_read_b128 v[204:207], v161 offset:18432
	ds_read_b128 v[208:211], v162 offset:16384
	ds_read_b128 v[212:215], v162 offset:18432
	ds_read_b128 v[216:219], v161 offset:20480
	ds_read_b128 v[220:223], v161 offset:22528
	ds_read_b128 v[224:227], v162 offset:20480
	ds_read_b128 v[228:231], v162 offset:22528
	buffer_load_dwordx4 v153, s[8:11], s55 offen lds
	s_mov_b32 m0, s3
	s_add_i32 s61, s55, 0x80000
	buffer_load_dwordx4 v156, s[8:11], s55 offen lds
	s_mov_b32 m0, s20
	s_nop 0
	buffer_load_dwordx4 v153, s[8:11], s61 offen lds
	s_mov_b32 m0, s21
	s_nop 0
	buffer_load_dwordx4 v156, s[8:11], s61 offen lds
	s_mov_b32 m0, s1
	s_nop 0
	buffer_load_dwordx4 v151, s[48:51], s60 offen lds
	s_mov_b32 m0, s26
	s_nop 0
	buffer_load_dwordx4 v155, s[48:51], s60 offen lds
	s_waitcnt vmcnt(8)
	s_waitcnt lgkmcnt(0)
	s_barrier
	s_waitcnt lgkmcnt(0)
	v_mfma_f32_16x16x32_f16 v[54:57], v[164:167], v[196:199], v[54:57]
	v_mfma_f32_16x16x32_f16 v[66:69], v[168:171], v[196:199], v[66:69]
	v_mfma_f32_16x16x32_f16 v[30:33], v[164:167], v[204:207], v[30:33]
	v_mfma_f32_16x16x32_f16 v[38:41], v[168:171], v[204:207], v[38:41]
	v_mfma_f32_16x16x32_f16 v[10:13], v[164:167], v[216:219], v[10:13]
	v_mfma_f32_16x16x32_f16 v[18:21], v[168:171], v[216:219], v[18:21]
	v_mfma_f32_16x16x32_f16 v[2:5], v[164:167], v[220:223], v[2:5]
	v_mfma_f32_16x16x32_f16 v[6:9], v[168:171], v[220:223], v[6:9]
	v_mfma_f32_16x16x32_f16 v[54:57], v[172:175], v[208:211], v[54:57]
	v_mfma_f32_16x16x32_f16 v[66:69], v[176:179], v[208:211], v[66:69]
	v_mfma_f32_16x16x32_f16 v[30:33], v[172:175], v[212:215], v[30:33]
	v_mfma_f32_16x16x32_f16 v[38:41], v[176:179], v[212:215], v[38:41]
	v_mfma_f32_16x16x32_f16 v[10:13], v[172:175], v[224:227], v[10:13]
	v_mfma_f32_16x16x32_f16 v[18:21], v[176:179], v[224:227], v[18:21]
	v_mfma_f32_16x16x32_f16 v[2:5], v[172:175], v[228:231], v[2:5]
	v_mfma_f32_16x16x32_f16 v[6:9], v[176:179], v[228:231], v[6:9]
	v_mfma_f32_16x16x32_f16 v[106:109], v[180:183], v[196:199], v[106:109]
	v_mfma_f32_16x16x32_f16 v[114:117], v[184:187], v[196:199], v[114:117]
	v_mfma_f32_16x16x32_f16 v[82:85], v[180:183], v[204:207], v[82:85]
	v_mfma_f32_16x16x32_f16 v[90:93], v[184:187], v[204:207], v[90:93]
	v_mfma_f32_16x16x32_f16 v[46:49], v[180:183], v[216:219], v[46:49]
	v_mfma_f32_16x16x32_f16 v[58:61], v[184:187], v[216:219], v[58:61]
	v_mfma_f32_16x16x32_f16 v[26:29], v[180:183], v[220:223], v[26:29]
	v_mfma_f32_16x16x32_f16 v[50:53], v[184:187], v[220:223], v[50:53]
	v_mfma_f32_16x16x32_f16 v[106:109], v[188:191], v[208:211], v[106:109]
	v_mfma_f32_16x16x32_f16 v[114:117], v[192:195], v[208:211], v[114:117]
	v_mfma_f32_16x16x32_f16 v[82:85], v[188:191], v[212:215], v[82:85]
	v_mfma_f32_16x16x32_f16 v[90:93], v[192:195], v[212:215], v[90:93]
	v_mfma_f32_16x16x32_f16 v[46:49], v[188:191], v[224:227], v[46:49]
	v_mfma_f32_16x16x32_f16 v[58:61], v[192:195], v[224:227], v[58:61]
	v_mfma_f32_16x16x32_f16 v[26:29], v[188:191], v[228:231], v[26:29]
	v_mfma_f32_16x16x32_f16 v[50:53], v[192:195], v[228:231], v[50:53]
	s_barrier
	s_add_i32 s61, 0, 0x18000
	v_add_u32_e32 v0, s61, v157
	v_add_u32_e32 v147, s61, v158
	s_add_i32 s61, 0, 0x1c000
	ds_read_b128 v[164:167], v0
	ds_read_b128 v[168:171], v0 offset:2048
	ds_read_b128 v[172:175], v147
	ds_read_b128 v[176:179], v147 offset:2048
	v_add_u32_e32 v0, s61, v157
	v_add_u32_e32 v147, s61, v158
	ds_read_b128 v[180:183], v0
	ds_read_b128 v[184:187], v0 offset:2048
	ds_read_b128 v[188:191], v147
	ds_read_b128 v[192:195], v147 offset:2048
	s_add_i32 s60, s60, 0x80000
	s_mov_b32 m0, s27
	ds_read_b128 v[196:199], v161 offset:32768
	ds_read_b128 v[204:207], v161 offset:34816
	ds_read_b128 v[208:211], v162 offset:32768
	ds_read_b128 v[212:215], v162 offset:34816
	ds_read_b128 v[216:219], v161 offset:36864
	ds_read_b128 v[220:223], v161 offset:38912
	ds_read_b128 v[224:227], v162 offset:36864
	ds_read_b128 v[228:231], v162 offset:38912
	buffer_load_dwordx4 v151, s[48:51], s60 offen lds
	s_mov_b32 m0, s28
	s_nop 0
	buffer_load_dwordx4 v155, s[48:51], s60 offen lds
	s_waitcnt vmcnt(8)
	s_waitcnt lgkmcnt(0)
	s_barrier
	s_waitcnt lgkmcnt(0)
	v_mfma_f32_16x16x32_f16 v[94:97], v[164:167], v[196:199], v[94:97]
	v_mfma_f32_16x16x32_f16 v[98:101], v[168:171], v[196:199], v[98:101]
	v_mfma_f32_16x16x32_f16 v[62:65], v[164:167], v[204:207], v[62:65]
	v_mfma_f32_16x16x32_f16 v[74:77], v[168:171], v[204:207], v[74:77]
	v_mfma_f32_16x16x32_f16 v[34:37], v[164:167], v[216:219], v[34:37]
	v_mfma_f32_16x16x32_f16 v[42:45], v[168:171], v[216:219], v[42:45]
	v_mfma_f32_16x16x32_f16 v[14:17], v[164:167], v[220:223], v[14:17]
	v_mfma_f32_16x16x32_f16 v[22:25], v[168:171], v[220:223], v[22:25]
	v_mfma_f32_16x16x32_f16 v[94:97], v[172:175], v[208:211], v[94:97]
	v_mfma_f32_16x16x32_f16 v[98:101], v[176:179], v[208:211], v[98:101]
	v_mfma_f32_16x16x32_f16 v[62:65], v[172:175], v[212:215], v[62:65]
	v_mfma_f32_16x16x32_f16 v[74:77], v[176:179], v[212:215], v[74:77]
	v_mfma_f32_16x16x32_f16 v[34:37], v[172:175], v[224:227], v[34:37]
	v_mfma_f32_16x16x32_f16 v[42:45], v[176:179], v[224:227], v[42:45]
	v_mfma_f32_16x16x32_f16 v[14:17], v[172:175], v[228:231], v[14:17]
	v_mfma_f32_16x16x32_f16 v[22:25], v[176:179], v[228:231], v[22:25]
	v_mfma_f32_16x16x32_f16 v[122:125], v[180:183], v[196:199], v[122:125]
	v_mfma_f32_16x16x32_f16 v[126:129], v[184:187], v[196:199], v[126:129]
	v_mfma_f32_16x16x32_f16 v[110:113], v[180:183], v[204:207], v[110:113]
	v_mfma_f32_16x16x32_f16 v[118:121], v[184:187], v[204:207], v[118:121]
	v_mfma_f32_16x16x32_f16 v[86:89], v[180:183], v[216:219], v[86:89]
	v_mfma_f32_16x16x32_f16 v[102:105], v[184:187], v[216:219], v[102:105]
	v_mfma_f32_16x16x32_f16 v[70:73], v[180:183], v[220:223], v[70:73]
	v_mfma_f32_16x16x32_f16 v[78:81], v[184:187], v[220:223], v[78:81]
	v_mfma_f32_16x16x32_f16 v[122:125], v[188:191], v[208:211], v[122:125]
	v_mfma_f32_16x16x32_f16 v[126:129], v[192:195], v[208:211], v[126:129]
	v_mfma_f32_16x16x32_f16 v[110:113], v[188:191], v[212:215], v[110:113]
	v_mfma_f32_16x16x32_f16 v[118:121], v[192:195], v[212:215], v[118:121]
	v_mfma_f32_16x16x32_f16 v[86:89], v[188:191], v[224:227], v[86:89]
	v_mfma_f32_16x16x32_f16 v[102:105], v[192:195], v[224:227], v[102:105]
	v_mfma_f32_16x16x32_f16 v[70:73], v[188:191], v[228:231], v[70:73]
	v_mfma_f32_16x16x32_f16 v[78:81], v[192:195], v[228:231], v[78:81]
	s_barrier
	s_mov_b32 m0, s29
	ds_read_b128 v[196:199], v161 offset:49152
	ds_read_b128 v[204:207], v161 offset:51200
	ds_read_b128 v[208:211], v162 offset:49152
	ds_read_b128 v[212:215], v162 offset:51200
	ds_read_b128 v[216:219], v161 offset:53248
	ds_read_b128 v[220:223], v161 offset:55296
	ds_read_b128 v[224:227], v162 offset:53248
	ds_read_b128 v[228:231], v162 offset:55296
	buffer_load_dwordx4 v153, s[8:11], s58 offen lds
	s_mov_b32 m0, s30
	s_add_i32 s55, s55, 0x80080
	buffer_load_dwordx4 v156, s[8:11], s58 offen lds
	s_mov_b32 m0, s35
	s_nop 0
	buffer_load_dwordx4 v153, s[8:11], s55 offen lds
	s_mov_b32 m0, s36
	s_nop 0
	buffer_load_dwordx4 v156, s[8:11], s55 offen lds
	s_mov_b32 m0, s31
	s_nop 0
	buffer_load_dwordx4 v151, s[48:51], s56 offen lds
	s_mov_b32 m0, s34
	s_nop 0
	buffer_load_dwordx4 v155, s[48:51], s56 offen lds
	s_waitcnt vmcnt(8)
	s_waitcnt lgkmcnt(0)
	s_barrier
	s_waitcnt lgkmcnt(0)
	v_mfma_f32_16x16x32_f16 v[54:57], v[164:167], v[196:199], v[54:57]
	v_mfma_f32_16x16x32_f16 v[66:69], v[168:171], v[196:199], v[66:69]
	v_mfma_f32_16x16x32_f16 v[30:33], v[164:167], v[204:207], v[30:33]
	v_mfma_f32_16x16x32_f16 v[38:41], v[168:171], v[204:207], v[38:41]
	v_mfma_f32_16x16x32_f16 v[10:13], v[164:167], v[216:219], v[10:13]
	v_mfma_f32_16x16x32_f16 v[18:21], v[168:171], v[216:219], v[18:21]
	v_mfma_f32_16x16x32_f16 v[2:5], v[164:167], v[220:223], v[2:5]
	v_mfma_f32_16x16x32_f16 v[6:9], v[168:171], v[220:223], v[6:9]
	v_mfma_f32_16x16x32_f16 v[54:57], v[172:175], v[208:211], v[54:57]
	v_mfma_f32_16x16x32_f16 v[66:69], v[176:179], v[208:211], v[66:69]
	v_mfma_f32_16x16x32_f16 v[30:33], v[172:175], v[212:215], v[30:33]
	v_mfma_f32_16x16x32_f16 v[38:41], v[176:179], v[212:215], v[38:41]
	v_mfma_f32_16x16x32_f16 v[10:13], v[172:175], v[224:227], v[10:13]
	v_mfma_f32_16x16x32_f16 v[18:21], v[176:179], v[224:227], v[18:21]
	v_mfma_f32_16x16x32_f16 v[2:5], v[172:175], v[228:231], v[2:5]
	v_mfma_f32_16x16x32_f16 v[6:9], v[176:179], v[228:231], v[6:9]
	v_mfma_f32_16x16x32_f16 v[106:109], v[180:183], v[196:199], v[106:109]
	v_mfma_f32_16x16x32_f16 v[114:117], v[184:187], v[196:199], v[114:117]
	v_mfma_f32_16x16x32_f16 v[82:85], v[180:183], v[204:207], v[82:85]
	v_mfma_f32_16x16x32_f16 v[90:93], v[184:187], v[204:207], v[90:93]
	v_mfma_f32_16x16x32_f16 v[46:49], v[180:183], v[216:219], v[46:49]
	v_mfma_f32_16x16x32_f16 v[58:61], v[184:187], v[216:219], v[58:61]
	v_mfma_f32_16x16x32_f16 v[26:29], v[180:183], v[220:223], v[26:29]
	v_mfma_f32_16x16x32_f16 v[50:53], v[184:187], v[220:223], v[50:53]
	v_mfma_f32_16x16x32_f16 v[106:109], v[188:191], v[208:211], v[106:109]
	v_mfma_f32_16x16x32_f16 v[114:117], v[192:195], v[208:211], v[114:117]
	v_mfma_f32_16x16x32_f16 v[82:85], v[188:191], v[212:215], v[82:85]
	v_mfma_f32_16x16x32_f16 v[90:93], v[192:195], v[212:215], v[90:93]
	v_mfma_f32_16x16x32_f16 v[46:49], v[188:191], v[224:227], v[46:49]
	v_mfma_f32_16x16x32_f16 v[58:61], v[192:195], v[224:227], v[58:61]
	v_mfma_f32_16x16x32_f16 v[26:29], v[188:191], v[228:231], v[26:29]
	v_mfma_f32_16x16x32_f16 v[50:53], v[192:195], v[228:231], v[50:53]
	s_barrier

.Lc0r_final:
	s_add_i32 s81, s64, 0x80
	s_and_b64 s[10:11], s[10:11], exec
	s_cselect_b32 s84, s24, s81
	s_cselect_b32 s85, s25, s65
	s_add_i32 s10, 0, 0x10000
	v_add_u32_e32 v3, s10, v208
	v_add_u32_e32 v144, s10, v209
	s_add_i32 s10, 0, 0x14000
	ds_read_b128 v[116:119], v3
	ds_read_b128 v[120:123], v3 offset:2048
	ds_read_b128 v[140:143], v144
	ds_read_b128 v[144:147], v144 offset:2048
	v_add_u32_e32 v3, s10, v208
	v_add_u32_e32 v176, s10, v209
	ds_read_b128 v[164:167], v3
	ds_read_b128 v[168:171], v3 offset:2048
	ds_read_b128 v[172:175], v176
	ds_read_b128 v[176:179], v176 offset:2048
	s_add_i32 s81, s84, 0x80
	s_add_i32 s82, s85, 0x80
	s_add_i32 s10, s29, s64
	s_mov_b32 m0, s53
	ds_read_b128 v[180:183], v214
	ds_read_b128 v[184:187], v214 offset:2048
	ds_read_b128 v[188:191], v215
	ds_read_b128 v[192:195], v215 offset:2048
	ds_read_b128 v[196:199], v214 offset:4096
	ds_read_b128 v[216:219], v214 offset:6144
	ds_read_b128 v[220:223], v215 offset:4096
	ds_read_b128 v[224:227], v215 offset:6144
	buffer_load_dwordx4 v204, s[48:51], s10 offen lds
	s_mov_b32 m0, s54
	s_nop 0
	buffer_load_dwordx4 v206, s[48:51], s10 offen lds
	s_waitcnt vmcnt(12)
	s_waitcnt lgkmcnt(0)
	s_barrier
	s_waitcnt lgkmcnt(0)
	v_mfma_f32_16x16x32_bf16 v[160:163], v[116:119], v[180:183], v[160:163]
	v_mfma_f32_16x16x32_bf16 v[152:155], v[120:123], v[180:183], v[152:155]
	v_mfma_f32_16x16x32_bf16 v[132:135], v[116:119], v[184:187], v[132:135]
	v_mfma_f32_16x16x32_bf16 v[124:127], v[120:123], v[184:187], v[124:127]
	v_mfma_f32_16x16x32_bf16 v[108:111], v[116:119], v[196:199], v[108:111]
	v_mfma_f32_16x16x32_bf16 v[100:103], v[120:123], v[196:199], v[100:103]
	v_mfma_f32_16x16x32_bf16 v[92:95], v[116:119], v[216:219], v[92:95]
	v_mfma_f32_16x16x32_bf16 v[84:87], v[120:123], v[216:219], v[84:87]
	v_mfma_f32_16x16x32_bf16 v[160:163], v[140:143], v[188:191], v[160:163]
	v_mfma_f32_16x16x32_bf16 v[152:155], v[144:147], v[188:191], v[152:155]
	v_mfma_f32_16x16x32_bf16 v[132:135], v[140:143], v[192:195], v[132:135]
	v_mfma_f32_16x16x32_bf16 v[124:127], v[144:147], v[192:195], v[124:127]
	v_mfma_f32_16x16x32_bf16 v[108:111], v[140:143], v[220:223], v[108:111]
	v_mfma_f32_16x16x32_bf16 v[100:103], v[144:147], v[220:223], v[100:103]
	v_mfma_f32_16x16x32_bf16 v[92:95], v[140:143], v[224:227], v[92:95]
	v_mfma_f32_16x16x32_bf16 v[84:87], v[144:147], v[224:227], v[84:87]
	v_mfma_f32_16x16x32_bf16 v[156:159], v[164:167], v[180:183], v[156:159]
	v_mfma_f32_16x16x32_bf16 v[148:151], v[168:171], v[180:183], v[148:151]
	v_mfma_f32_16x16x32_bf16 v[136:139], v[164:167], v[184:187], v[136:139]
	v_mfma_f32_16x16x32_bf16 v[128:131], v[168:171], v[184:187], v[128:131]
	v_mfma_f32_16x16x32_bf16 v[112:115], v[164:167], v[196:199], v[112:115]
	v_mfma_f32_16x16x32_bf16 v[104:107], v[168:171], v[196:199], v[104:107]
	v_mfma_f32_16x16x32_bf16 v[96:99], v[164:167], v[216:219], v[96:99]
	v_mfma_f32_16x16x32_bf16 v[88:91], v[168:171], v[216:219], v[88:91]
	v_mfma_f32_16x16x32_bf16 v[156:159], v[172:175], v[188:191], v[156:159]
	v_mfma_f32_16x16x32_bf16 v[148:151], v[176:179], v[188:191], v[148:151]
	v_mfma_f32_16x16x32_bf16 v[136:139], v[172:175], v[192:195], v[136:139]
	v_mfma_f32_16x16x32_bf16 v[128:131], v[176:179], v[192:195], v[128:131]
	v_mfma_f32_16x16x32_bf16 v[112:115], v[172:175], v[220:223], v[112:115]
	v_mfma_f32_16x16x32_bf16 v[104:107], v[176:179], v[220:223], v[104:107]
	v_mfma_f32_16x16x32_bf16 v[96:99], v[172:175], v[224:227], v[96:99]
	v_mfma_f32_16x16x32_bf16 v[88:91], v[176:179], v[224:227], v[88:91]
	s_barrier
	s_mov_b32 s10, s50
	s_mov_b32 s11, s51
	ds_read_b128 v[180:183], v214 offset:16384
	ds_read_b128 v[184:187], v214 offset:18432
	ds_read_b128 v[188:191], v215 offset:16384
	ds_read_b128 v[192:195], v215 offset:18432
	ds_read_b128 v[196:199], v214 offset:20480
	ds_read_b128 v[216:219], v214 offset:22528
	ds_read_b128 v[220:223], v215 offset:20480
	ds_read_b128 v[224:227], v215 offset:22528
	s_add_i32 s85, s85, s29
	s_waitcnt vmcnt(6)
	s_waitcnt lgkmcnt(0)
	s_barrier
	s_waitcnt lgkmcnt(0)
	v_mfma_f32_16x16x32_bf16 v[76:79], v[116:119], v[180:183], v[76:79]
	v_mfma_f32_16x16x32_bf16 v[68:71], v[120:123], v[180:183], v[68:71]
	v_mfma_f32_16x16x32_bf16 v[60:63], v[116:119], v[184:187], v[60:63]
	v_mfma_f32_16x16x32_bf16 v[52:55], v[120:123], v[184:187], v[52:55]
	v_mfma_f32_16x16x32_bf16 v[44:47], v[116:119], v[196:199], v[44:47]
	v_mfma_f32_16x16x32_bf16 v[36:39], v[120:123], v[196:199], v[36:39]
	v_mfma_f32_16x16x32_bf16 v[24:27], v[116:119], v[216:219], v[24:27]
	v_mfma_f32_16x16x32_bf16 v[20:23], v[120:123], v[216:219], v[20:23]
	v_mfma_f32_16x16x32_bf16 v[76:79], v[140:143], v[188:191], v[76:79]
	v_mfma_f32_16x16x32_bf16 v[68:71], v[144:147], v[188:191], v[68:71]
	v_mfma_f32_16x16x32_bf16 v[60:63], v[140:143], v[192:195], v[60:63]
	v_mfma_f32_16x16x32_bf16 v[52:55], v[144:147], v[192:195], v[52:55]
	v_mfma_f32_16x16x32_bf16 v[44:47], v[140:143], v[220:223], v[44:47]
	v_mfma_f32_16x16x32_bf16 v[36:39], v[144:147], v[220:223], v[36:39]
	v_mfma_f32_16x16x32_bf16 v[24:27], v[140:143], v[224:227], v[24:27]
	v_mfma_f32_16x16x32_bf16 v[20:23], v[144:147], v[224:227], v[20:23]
	v_mfma_f32_16x16x32_bf16 v[80:83], v[164:167], v[180:183], v[80:83]
	v_mfma_f32_16x16x32_bf16 v[72:75], v[168:171], v[180:183], v[72:75]
	v_mfma_f32_16x16x32_bf16 v[64:67], v[164:167], v[184:187], v[64:67]
	v_mfma_f32_16x16x32_bf16 v[56:59], v[168:171], v[184:187], v[56:59]
	v_mfma_f32_16x16x32_bf16 v[48:51], v[164:167], v[196:199], v[48:51]
	v_mfma_f32_16x16x32_bf16 v[40:43], v[168:171], v[196:199], v[40:43]
	v_mfma_f32_16x16x32_bf16 v[28:31], v[164:167], v[216:219], v[28:31]
	v_mfma_f32_16x16x32_bf16 v[32:35], v[168:171], v[216:219], v[32:35]
	v_mfma_f32_16x16x32_bf16 v[80:83], v[172:175], v[188:191], v[80:83]
	v_mfma_f32_16x16x32_bf16 v[72:75], v[176:179], v[188:191], v[72:75]
	v_mfma_f32_16x16x32_bf16 v[64:67], v[172:175], v[192:195], v[64:67]
	v_mfma_f32_16x16x32_bf16 v[56:59], v[176:179], v[192:195], v[56:59]
	v_mfma_f32_16x16x32_bf16 v[48:51], v[172:175], v[220:223], v[48:51]
	v_mfma_f32_16x16x32_bf16 v[40:43], v[176:179], v[220:223], v[40:43]
	v_mfma_f32_16x16x32_bf16 v[28:31], v[172:175], v[224:227], v[28:31]
	v_mfma_f32_16x16x32_bf16 v[32:35], v[176:179], v[224:227], v[32:35]
	s_barrier
	s_add_i32 s85, 0, 0x18000
	v_add_u32_e32 v3, s85, v208
	v_add_u32_e32 v144, s85, v209
	s_add_i32 s85, 0, 0x1c000
	ds_read_b128 v[116:119], v3
	ds_read_b128 v[120:123], v3 offset:2048
	ds_read_b128 v[140:143], v144
	ds_read_b128 v[144:147], v144 offset:2048
	v_add_u32_e32 v3, s85, v208
	v_add_u32_e32 v176, s85, v209
	ds_read_b128 v[164:167], v3
	ds_read_b128 v[168:171], v3 offset:2048
	ds_read_b128 v[172:175], v176
	ds_read_b128 v[176:179], v176 offset:2048
	s_add_i32 s84, s84, s29
	ds_read_b128 v[180:183], v214 offset:32768
	ds_read_b128 v[184:187], v214 offset:34816
	ds_read_b128 v[188:191], v215 offset:32768
	ds_read_b128 v[192:195], v215 offset:34816
	ds_read_b128 v[196:199], v214 offset:36864
	ds_read_b128 v[216:219], v214 offset:38912
	ds_read_b128 v[220:223], v215 offset:36864
	ds_read_b128 v[224:227], v215 offset:38912
	s_waitcnt vmcnt(0)
	s_waitcnt lgkmcnt(0)
	s_barrier
	s_waitcnt lgkmcnt(0)
	v_mfma_f32_16x16x32_bf16 v[160:163], v[116:119], v[180:183], v[160:163]
	v_mfma_f32_16x16x32_bf16 v[152:155], v[120:123], v[180:183], v[152:155]
	v_mfma_f32_16x16x32_bf16 v[132:135], v[116:119], v[184:187], v[132:135]
	v_mfma_f32_16x16x32_bf16 v[124:127], v[120:123], v[184:187], v[124:127]
	v_mfma_f32_16x16x32_bf16 v[108:111], v[116:119], v[196:199], v[108:111]
	v_mfma_f32_16x16x32_bf16 v[100:103], v[120:123], v[196:199], v[100:103]
	v_mfma_f32_16x16x32_bf16 v[92:95], v[116:119], v[216:219], v[92:95]
	v_mfma_f32_16x16x32_bf16 v[84:87], v[120:123], v[216:219], v[84:87]
	v_mfma_f32_16x16x32_bf16 v[160:163], v[140:143], v[188:191], v[160:163]
	v_mfma_f32_16x16x32_bf16 v[152:155], v[144:147], v[188:191], v[152:155]
	v_mfma_f32_16x16x32_bf16 v[132:135], v[140:143], v[192:195], v[132:135]
	v_mfma_f32_16x16x32_bf16 v[124:127], v[144:147], v[192:195], v[124:127]
	v_mfma_f32_16x16x32_bf16 v[108:111], v[140:143], v[220:223], v[108:111]
	v_mfma_f32_16x16x32_bf16 v[100:103], v[144:147], v[220:223], v[100:103]
	v_mfma_f32_16x16x32_bf16 v[92:95], v[140:143], v[224:227], v[92:95]
	v_mfma_f32_16x16x32_bf16 v[84:87], v[144:147], v[224:227], v[84:87]
	v_mfma_f32_16x16x32_bf16 v[156:159], v[164:167], v[180:183], v[156:159]
	v_mfma_f32_16x16x32_bf16 v[148:151], v[168:171], v[180:183], v[148:151]
	v_mfma_f32_16x16x32_bf16 v[136:139], v[164:167], v[184:187], v[136:139]
	v_mfma_f32_16x16x32_bf16 v[128:131], v[168:171], v[184:187], v[128:131]
	v_mfma_f32_16x16x32_bf16 v[112:115], v[164:167], v[196:199], v[112:115]
	v_mfma_f32_16x16x32_bf16 v[104:107], v[168:171], v[196:199], v[104:107]
	v_mfma_f32_16x16x32_bf16 v[96:99], v[164:167], v[216:219], v[96:99]
	v_mfma_f32_16x16x32_bf16 v[88:91], v[168:171], v[216:219], v[88:91]
	v_mfma_f32_16x16x32_bf16 v[156:159], v[172:175], v[188:191], v[156:159]
	v_mfma_f32_16x16x32_bf16 v[148:151], v[176:179], v[188:191], v[148:151]
	v_mfma_f32_16x16x32_bf16 v[136:139], v[172:175], v[192:195], v[136:139]
	v_mfma_f32_16x16x32_bf16 v[128:131], v[176:179], v[192:195], v[128:131]
	v_mfma_f32_16x16x32_bf16 v[112:115], v[172:175], v[220:223], v[112:115]
	v_mfma_f32_16x16x32_bf16 v[104:107], v[176:179], v[220:223], v[104:107]
	v_mfma_f32_16x16x32_bf16 v[96:99], v[172:175], v[224:227], v[96:99]
	v_mfma_f32_16x16x32_bf16 v[88:91], v[176:179], v[224:227], v[88:91]
	s_barrier
	ds_read_b128 v[180:183], v214 offset:49152
	ds_read_b128 v[184:187], v214 offset:51200
	ds_read_b128 v[188:191], v215 offset:49152
	ds_read_b128 v[192:195], v215 offset:51200
	ds_read_b128 v[196:199], v214 offset:53248
	ds_read_b128 v[216:219], v214 offset:55296
	ds_read_b128 v[220:223], v215 offset:53248
	ds_read_b128 v[224:227], v215 offset:55296
	s_add_i32 s82, s82, s29
	s_waitcnt vmcnt(0)
	s_waitcnt lgkmcnt(0)
	s_barrier
	s_waitcnt lgkmcnt(0)
	v_mfma_f32_16x16x32_bf16 v[76:79], v[116:119], v[180:183], v[76:79]
	v_mfma_f32_16x16x32_bf16 v[68:71], v[120:123], v[180:183], v[68:71]
	v_mfma_f32_16x16x32_bf16 v[60:63], v[116:119], v[184:187], v[60:63]
	v_mfma_f32_16x16x32_bf16 v[52:55], v[120:123], v[184:187], v[52:55]
	v_mfma_f32_16x16x32_bf16 v[44:47], v[116:119], v[196:199], v[44:47]
	v_mfma_f32_16x16x32_bf16 v[36:39], v[120:123], v[196:199], v[36:39]
	v_mfma_f32_16x16x32_bf16 v[24:27], v[116:119], v[216:219], v[24:27]
	v_mfma_f32_16x16x32_bf16 v[20:23], v[120:123], v[216:219], v[20:23]
	v_mfma_f32_16x16x32_bf16 v[76:79], v[140:143], v[188:191], v[76:79]
	v_mfma_f32_16x16x32_bf16 v[68:71], v[144:147], v[188:191], v[68:71]
	v_mfma_f32_16x16x32_bf16 v[60:63], v[140:143], v[192:195], v[60:63]
	v_mfma_f32_16x16x32_bf16 v[52:55], v[144:147], v[192:195], v[52:55]
	v_mfma_f32_16x16x32_bf16 v[44:47], v[140:143], v[220:223], v[44:47]
	v_mfma_f32_16x16x32_bf16 v[36:39], v[144:147], v[220:223], v[36:39]
	v_mfma_f32_16x16x32_bf16 v[24:27], v[140:143], v[224:227], v[24:27]
	v_mfma_f32_16x16x32_bf16 v[20:23], v[144:147], v[224:227], v[20:23]
	v_mfma_f32_16x16x32_bf16 v[80:83], v[164:167], v[180:183], v[80:83]
	v_mfma_f32_16x16x32_bf16 v[72:75], v[168:171], v[180:183], v[72:75]
	v_mfma_f32_16x16x32_bf16 v[64:67], v[164:167], v[184:187], v[64:67]
	v_mfma_f32_16x16x32_bf16 v[56:59], v[168:171], v[184:187], v[56:59]
	v_mfma_f32_16x16x32_bf16 v[48:51], v[164:167], v[196:199], v[48:51]
	v_mfma_f32_16x16x32_bf16 v[40:43], v[168:171], v[196:199], v[40:43]
	v_mfma_f32_16x16x32_bf16 v[28:31], v[164:167], v[216:219], v[28:31]
	v_mfma_f32_16x16x32_bf16 v[32:35], v[168:171], v[216:219], v[32:35]
	v_mfma_f32_16x16x32_bf16 v[80:83], v[172:175], v[188:191], v[80:83]
	v_mfma_f32_16x16x32_bf16 v[72:75], v[176:179], v[188:191], v[72:75]
	v_mfma_f32_16x16x32_bf16 v[64:67], v[172:175], v[192:195], v[64:67]
	v_mfma_f32_16x16x32_bf16 v[56:59], v[176:179], v[192:195], v[56:59]
	v_mfma_f32_16x16x32_bf16 v[48:51], v[172:175], v[220:223], v[48:51]
	v_mfma_f32_16x16x32_bf16 v[40:43], v[176:179], v[220:223], v[40:43]
	v_mfma_f32_16x16x32_bf16 v[28:31], v[172:175], v[224:227], v[28:31]
	v_mfma_f32_16x16x32_bf16 v[32:35], v[176:179], v[224:227], v[32:35]
	s_barrier
	s_branch .Lc0r_tail
.Lc0r_last:
	s_add_i32 s81, s64, 0x80
	s_and_b64 s[10:11], s[10:11], exec
	s_cselect_b32 s84, s24, s81
	s_cselect_b32 s85, s25, s65
	s_add_i32 s10, 0, 0x10000
	v_add_u32_e32 v3, s10, v208
	v_add_u32_e32 v144, s10, v209
	s_add_i32 s10, 0, 0x14000
	ds_read_b128 v[116:119], v3
	ds_read_b128 v[120:123], v3 offset:2048
	ds_read_b128 v[140:143], v144
	ds_read_b128 v[144:147], v144 offset:2048
	v_add_u32_e32 v3, s10, v208
	v_add_u32_e32 v176, s10, v209
	ds_read_b128 v[164:167], v3
	ds_read_b128 v[168:171], v3 offset:2048
	ds_read_b128 v[172:175], v176
	ds_read_b128 v[176:179], v176 offset:2048
	s_add_i32 s81, s84, 0x80
	s_add_i32 s82, s85, 0x80
	s_add_i32 s10, s29, s64
	s_mov_b32 m0, s53
	ds_read_b128 v[180:183], v214
	ds_read_b128 v[184:187], v214 offset:2048
	ds_read_b128 v[188:191], v215
	ds_read_b128 v[192:195], v215 offset:2048
	ds_read_b128 v[196:199], v214 offset:4096
	ds_read_b128 v[216:219], v214 offset:6144
	ds_read_b128 v[220:223], v215 offset:4096
	ds_read_b128 v[224:227], v215 offset:6144
	buffer_load_dwordx4 v204, s[48:51], s10 offen lds
	s_mov_b32 m0, s54
	s_nop 0
	buffer_load_dwordx4 v206, s[48:51], s10 offen lds
	s_waitcnt vmcnt(12)
	s_waitcnt lgkmcnt(0)
	s_barrier
	s_waitcnt lgkmcnt(0)
	v_mfma_f32_16x16x32_bf16 v[160:163], v[116:119], v[180:183], v[160:163]
	v_mfma_f32_16x16x32_bf16 v[152:155], v[120:123], v[180:183], v[152:155]
	v_mfma_f32_16x16x32_bf16 v[132:135], v[116:119], v[184:187], v[132:135]
	v_mfma_f32_16x16x32_bf16 v[124:127], v[120:123], v[184:187], v[124:127]
	v_mfma_f32_16x16x32_bf16 v[108:111], v[116:119], v[196:199], v[108:111]
	v_mfma_f32_16x16x32_bf16 v[100:103], v[120:123], v[196:199], v[100:103]
	v_mfma_f32_16x16x32_bf16 v[92:95], v[116:119], v[216:219], v[92:95]
	v_mfma_f32_16x16x32_bf16 v[84:87], v[120:123], v[216:219], v[84:87]
	v_mfma_f32_16x16x32_bf16 v[160:163], v[140:143], v[188:191], v[160:163]
	v_mfma_f32_16x16x32_bf16 v[152:155], v[144:147], v[188:191], v[152:155]
	v_mfma_f32_16x16x32_bf16 v[132:135], v[140:143], v[192:195], v[132:135]
	v_mfma_f32_16x16x32_bf16 v[124:127], v[144:147], v[192:195], v[124:127]
	v_mfma_f32_16x16x32_bf16 v[108:111], v[140:143], v[220:223], v[108:111]
	v_mfma_f32_16x16x32_bf16 v[100:103], v[144:147], v[220:223], v[100:103]
	v_mfma_f32_16x16x32_bf16 v[92:95], v[140:143], v[224:227], v[92:95]
	v_mfma_f32_16x16x32_bf16 v[84:87], v[144:147], v[224:227], v[84:87]
	v_mfma_f32_16x16x32_bf16 v[156:159], v[164:167], v[180:183], v[156:159]
	v_mfma_f32_16x16x32_bf16 v[148:151], v[168:171], v[180:183], v[148:151]
	v_mfma_f32_16x16x32_bf16 v[136:139], v[164:167], v[184:187], v[136:139]
	v_mfma_f32_16x16x32_bf16 v[128:131], v[168:171], v[184:187], v[128:131]
	v_mfma_f32_16x16x32_bf16 v[112:115], v[164:167], v[196:199], v[112:115]
	v_mfma_f32_16x16x32_bf16 v[104:107], v[168:171], v[196:199], v[104:107]
	v_mfma_f32_16x16x32_bf16 v[96:99], v[164:167], v[216:219], v[96:99]
	v_mfma_f32_16x16x32_bf16 v[88:91], v[168:171], v[216:219], v[88:91]
	v_mfma_f32_16x16x32_bf16 v[156:159], v[172:175], v[188:191], v[156:159]
	v_mfma_f32_16x16x32_bf16 v[148:151], v[176:179], v[188:191], v[148:151]
	v_mfma_f32_16x16x32_bf16 v[136:139], v[172:175], v[192:195], v[136:139]
	v_mfma_f32_16x16x32_bf16 v[128:131], v[176:179], v[192:195], v[128:131]
	v_mfma_f32_16x16x32_bf16 v[112:115], v[172:175], v[220:223], v[112:115]
	v_mfma_f32_16x16x32_bf16 v[104:107], v[176:179], v[220:223], v[104:107]
	v_mfma_f32_16x16x32_bf16 v[96:99], v[172:175], v[224:227], v[96:99]
	v_mfma_f32_16x16x32_bf16 v[88:91], v[176:179], v[224:227], v[88:91]
	s_barrier
	s_mov_b32 m0, s34
	s_mov_b32 s10, s50
	s_mov_b32 s11, s51
	ds_read_b128 v[180:183], v214 offset:16384
	ds_read_b128 v[184:187], v214 offset:18432
	ds_read_b128 v[188:191], v215 offset:16384
	ds_read_b128 v[192:195], v215 offset:18432
	ds_read_b128 v[196:199], v214 offset:20480
	ds_read_b128 v[216:219], v214 offset:22528
	ds_read_b128 v[220:223], v215 offset:20480
	ds_read_b128 v[224:227], v215 offset:22528
	buffer_load_dwordx4 v205, s[8:11], s85 offen lds
	s_mov_b32 m0, s35
	s_nop 0
	buffer_load_dwordx4 v207, s[8:11], s85 offen lds
	s_add_i32 s85, s85, s29
	s_mov_b32 m0, s36
	s_nop 0
	buffer_load_dwordx4 v205, s[8:11], s85 offen lds
	s_mov_b32 m0, s37
	s_nop 0
	buffer_load_dwordx4 v207, s[8:11], s85 offen lds
	s_mov_b32 m0, s31
	s_nop 0
	buffer_load_dwordx4 v204, s[48:51], s84 offen lds
	s_mov_b32 m0, s38
	s_nop 0
	buffer_load_dwordx4 v206, s[48:51], s84 offen lds
	s_waitcnt vmcnt(12)
	s_waitcnt lgkmcnt(0)
	s_barrier
	s_waitcnt lgkmcnt(0)
	v_mfma_f32_16x16x32_bf16 v[76:79], v[116:119], v[180:183], v[76:79]
	v_mfma_f32_16x16x32_bf16 v[68:71], v[120:123], v[180:183], v[68:71]
	v_mfma_f32_16x16x32_bf16 v[60:63], v[116:119], v[184:187], v[60:63]
	v_mfma_f32_16x16x32_bf16 v[52:55], v[120:123], v[184:187], v[52:55]
	v_mfma_f32_16x16x32_bf16 v[44:47], v[116:119], v[196:199], v[44:47]
	v_mfma_f32_16x16x32_bf16 v[36:39], v[120:123], v[196:199], v[36:39]
	v_mfma_f32_16x16x32_bf16 v[24:27], v[116:119], v[216:219], v[24:27]
	v_mfma_f32_16x16x32_bf16 v[20:23], v[120:123], v[216:219], v[20:23]
	v_mfma_f32_16x16x32_bf16 v[76:79], v[140:143], v[188:191], v[76:79]
	v_mfma_f32_16x16x32_bf16 v[68:71], v[144:147], v[188:191], v[68:71]
	v_mfma_f32_16x16x32_bf16 v[60:63], v[140:143], v[192:195], v[60:63]
	v_mfma_f32_16x16x32_bf16 v[52:55], v[144:147], v[192:195], v[52:55]
	v_mfma_f32_16x16x32_bf16 v[44:47], v[140:143], v[220:223], v[44:47]
	v_mfma_f32_16x16x32_bf16 v[36:39], v[144:147], v[220:223], v[36:39]
	v_mfma_f32_16x16x32_bf16 v[24:27], v[140:143], v[224:227], v[24:27]
	v_mfma_f32_16x16x32_bf16 v[20:23], v[144:147], v[224:227], v[20:23]
	v_mfma_f32_16x16x32_bf16 v[80:83], v[164:167], v[180:183], v[80:83]
	v_mfma_f32_16x16x32_bf16 v[72:75], v[168:171], v[180:183], v[72:75]
	v_mfma_f32_16x16x32_bf16 v[64:67], v[164:167], v[184:187], v[64:67]
	v_mfma_f32_16x16x32_bf16 v[56:59], v[168:171], v[184:187], v[56:59]
	v_mfma_f32_16x16x32_bf16 v[48:51], v[164:167], v[196:199], v[48:51]
	v_mfma_f32_16x16x32_bf16 v[40:43], v[168:171], v[196:199], v[40:43]
	v_mfma_f32_16x16x32_bf16 v[28:31], v[164:167], v[216:219], v[28:31]
	v_mfma_f32_16x16x32_bf16 v[32:35], v[168:171], v[216:219], v[32:35]
	v_mfma_f32_16x16x32_bf16 v[80:83], v[172:175], v[188:191], v[80:83]
	v_mfma_f32_16x16x32_bf16 v[72:75], v[176:179], v[188:191], v[72:75]
	v_mfma_f32_16x16x32_bf16 v[64:67], v[172:175], v[192:195], v[64:67]
	v_mfma_f32_16x16x32_bf16 v[56:59], v[176:179], v[192:195], v[56:59]
	v_mfma_f32_16x16x32_bf16 v[48:51], v[172:175], v[220:223], v[48:51]
	v_mfma_f32_16x16x32_bf16 v[40:43], v[176:179], v[220:223], v[40:43]
	v_mfma_f32_16x16x32_bf16 v[28:31], v[172:175], v[224:227], v[28:31]
	v_mfma_f32_16x16x32_bf16 v[32:35], v[176:179], v[224:227], v[32:35]
	s_barrier
	s_add_i32 s85, 0, 0x18000
	v_add_u32_e32 v3, s85, v208
	v_add_u32_e32 v144, s85, v209
	s_add_i32 s85, 0, 0x1c000
	ds_read_b128 v[116:119], v3
	ds_read_b128 v[120:123], v3 offset:2048
	ds_read_b128 v[140:143], v144
	ds_read_b128 v[144:147], v144 offset:2048
	v_add_u32_e32 v3, s85, v208
	v_add_u32_e32 v176, s85, v209
	ds_read_b128 v[164:167], v3
	ds_read_b128 v[168:171], v3 offset:2048
	ds_read_b128 v[172:175], v176
	ds_read_b128 v[176:179], v176 offset:2048
	s_add_i32 s84, s84, s29
	s_mov_b32 m0, s39
	ds_read_b128 v[180:183], v214 offset:32768
	ds_read_b128 v[184:187], v214 offset:34816
	ds_read_b128 v[188:191], v215 offset:32768
	ds_read_b128 v[192:195], v215 offset:34816
	ds_read_b128 v[196:199], v214 offset:36864
	ds_read_b128 v[216:219], v214 offset:38912
	ds_read_b128 v[220:223], v215 offset:36864
	ds_read_b128 v[224:227], v215 offset:38912
	buffer_load_dwordx4 v204, s[48:51], s84 offen lds
	s_mov_b32 m0, s40
	s_nop 0
	buffer_load_dwordx4 v206, s[48:51], s84 offen lds
	s_waitcnt vmcnt(8)
	s_waitcnt lgkmcnt(0)
	s_barrier
	s_waitcnt lgkmcnt(0)
	v_mfma_f32_16x16x32_bf16 v[160:163], v[116:119], v[180:183], v[160:163]
	v_mfma_f32_16x16x32_bf16 v[152:155], v[120:123], v[180:183], v[152:155]
	v_mfma_f32_16x16x32_bf16 v[132:135], v[116:119], v[184:187], v[132:135]
	v_mfma_f32_16x16x32_bf16 v[124:127], v[120:123], v[184:187], v[124:127]
	v_mfma_f32_16x16x32_bf16 v[108:111], v[116:119], v[196:199], v[108:111]
	v_mfma_f32_16x16x32_bf16 v[100:103], v[120:123], v[196:199], v[100:103]
	v_mfma_f32_16x16x32_bf16 v[92:95], v[116:119], v[216:219], v[92:95]
	v_mfma_f32_16x16x32_bf16 v[84:87], v[120:123], v[216:219], v[84:87]
	v_mfma_f32_16x16x32_bf16 v[160:163], v[140:143], v[188:191], v[160:163]
	v_mfma_f32_16x16x32_bf16 v[152:155], v[144:147], v[188:191], v[152:155]
	v_mfma_f32_16x16x32_bf16 v[132:135], v[140:143], v[192:195], v[132:135]
	v_mfma_f32_16x16x32_bf16 v[124:127], v[144:147], v[192:195], v[124:127]
	v_mfma_f32_16x16x32_bf16 v[108:111], v[140:143], v[220:223], v[108:111]
	v_mfma_f32_16x16x32_bf16 v[100:103], v[144:147], v[220:223], v[100:103]
	v_mfma_f32_16x16x32_bf16 v[92:95], v[140:143], v[224:227], v[92:95]
	v_mfma_f32_16x16x32_bf16 v[84:87], v[144:147], v[224:227], v[84:87]
	v_mfma_f32_16x16x32_bf16 v[156:159], v[164:167], v[180:183], v[156:159]
	v_mfma_f32_16x16x32_bf16 v[148:151], v[168:171], v[180:183], v[148:151]
	v_mfma_f32_16x16x32_bf16 v[136:139], v[164:167], v[184:187], v[136:139]
	v_mfma_f32_16x16x32_bf16 v[128:131], v[168:171], v[184:187], v[128:131]
	v_mfma_f32_16x16x32_bf16 v[112:115], v[164:167], v[196:199], v[112:115]
	v_mfma_f32_16x16x32_bf16 v[104:107], v[168:171], v[196:199], v[104:107]
	v_mfma_f32_16x16x32_bf16 v[96:99], v[164:167], v[216:219], v[96:99]
	v_mfma_f32_16x16x32_bf16 v[88:91], v[168:171], v[216:219], v[88:91]
	v_mfma_f32_16x16x32_bf16 v[156:159], v[172:175], v[188:191], v[156:159]
	v_mfma_f32_16x16x32_bf16 v[148:151], v[176:179], v[188:191], v[148:151]
	v_mfma_f32_16x16x32_bf16 v[136:139], v[172:175], v[192:195], v[136:139]
	v_mfma_f32_16x16x32_bf16 v[128:131], v[176:179], v[192:195], v[128:131]
	v_mfma_f32_16x16x32_bf16 v[112:115], v[172:175], v[220:223], v[112:115]
	v_mfma_f32_16x16x32_bf16 v[104:107], v[176:179], v[220:223], v[104:107]
	v_mfma_f32_16x16x32_bf16 v[96:99], v[172:175], v[224:227], v[96:99]
	v_mfma_f32_16x16x32_bf16 v[88:91], v[176:179], v[224:227], v[88:91]
	s_barrier
	s_mov_b32 m0, s41
	ds_read_b128 v[180:183], v214 offset:49152
	ds_read_b128 v[184:187], v214 offset:51200
	ds_read_b128 v[188:191], v215 offset:49152
	ds_read_b128 v[192:195], v215 offset:51200
	ds_read_b128 v[196:199], v214 offset:53248
	ds_read_b128 v[216:219], v214 offset:55296
	ds_read_b128 v[220:223], v215 offset:53248
	ds_read_b128 v[224:227], v215 offset:55296
	buffer_load_dwordx4 v205, s[8:11], s82 offen lds
	s_mov_b32 m0, s42
	s_nop 0
	buffer_load_dwordx4 v207, s[8:11], s82 offen lds
	s_add_i32 s82, s82, s29
	s_mov_b32 m0, s45
	s_nop 0
	buffer_load_dwordx4 v205, s[8:11], s82 offen lds
	s_mov_b32 m0, s46
	s_nop 0
	buffer_load_dwordx4 v207, s[8:11], s82 offen lds
	s_mov_b32 m0, s43
	s_nop 0
	buffer_load_dwordx4 v204, s[48:51], s81 offen lds
	s_mov_b32 m0, s44
	s_nop 0
	buffer_load_dwordx4 v206, s[48:51], s81 offen lds
	s_waitcnt vmcnt(8)
	s_waitcnt lgkmcnt(0)
	s_barrier
	s_waitcnt lgkmcnt(0)
	v_mfma_f32_16x16x32_bf16 v[76:79], v[116:119], v[180:183], v[76:79]
	v_mfma_f32_16x16x32_bf16 v[68:71], v[120:123], v[180:183], v[68:71]
	v_mfma_f32_16x16x32_bf16 v[60:63], v[116:119], v[184:187], v[60:63]
	v_mfma_f32_16x16x32_bf16 v[52:55], v[120:123], v[184:187], v[52:55]
	v_mfma_f32_16x16x32_bf16 v[44:47], v[116:119], v[196:199], v[44:47]
	v_mfma_f32_16x16x32_bf16 v[36:39], v[120:123], v[196:199], v[36:39]
	v_mfma_f32_16x16x32_bf16 v[24:27], v[116:119], v[216:219], v[24:27]
	v_mfma_f32_16x16x32_bf16 v[20:23], v[120:123], v[216:219], v[20:23]
	v_mfma_f32_16x16x32_bf16 v[76:79], v[140:143], v[188:191], v[76:79]
	v_mfma_f32_16x16x32_bf16 v[68:71], v[144:147], v[188:191], v[68:71]
	v_mfma_f32_16x16x32_bf16 v[60:63], v[140:143], v[192:195], v[60:63]
	v_mfma_f32_16x16x32_bf16 v[52:55], v[144:147], v[192:195], v[52:55]
	v_mfma_f32_16x16x32_bf16 v[44:47], v[140:143], v[220:223], v[44:47]
	v_mfma_f32_16x16x32_bf16 v[36:39], v[144:147], v[220:223], v[36:39]
	v_mfma_f32_16x16x32_bf16 v[24:27], v[140:143], v[224:227], v[24:27]
	v_mfma_f32_16x16x32_bf16 v[20:23], v[144:147], v[224:227], v[20:23]
	v_mfma_f32_16x16x32_bf16 v[80:83], v[164:167], v[180:183], v[80:83]
	v_mfma_f32_16x16x32_bf16 v[72:75], v[168:171], v[180:183], v[72:75]
	v_mfma_f32_16x16x32_bf16 v[64:67], v[164:167], v[184:187], v[64:67]
	v_mfma_f32_16x16x32_bf16 v[56:59], v[168:171], v[184:187], v[56:59]
	v_mfma_f32_16x16x32_bf16 v[48:51], v[164:167], v[196:199], v[48:51]
	v_mfma_f32_16x16x32_bf16 v[40:43], v[168:171], v[196:199], v[40:43]
	v_mfma_f32_16x16x32_bf16 v[28:31], v[164:167], v[216:219], v[28:31]
	v_mfma_f32_16x16x32_bf16 v[32:35], v[168:171], v[216:219], v[32:35]
	v_mfma_f32_16x16x32_bf16 v[80:83], v[172:175], v[188:191], v[80:83]
	v_mfma_f32_16x16x32_bf16 v[72:75], v[176:179], v[188:191], v[72:75]
	v_mfma_f32_16x16x32_bf16 v[64:67], v[172:175], v[192:195], v[64:67]
	v_mfma_f32_16x16x32_bf16 v[56:59], v[176:179], v[192:195], v[56:59]
	v_mfma_f32_16x16x32_bf16 v[48:51], v[172:175], v[220:223], v[48:51]
	v_mfma_f32_16x16x32_bf16 v[40:43], v[176:179], v[220:223], v[40:43]
	v_mfma_f32_16x16x32_bf16 v[28:31], v[172:175], v[224:227], v[28:31]
	v_mfma_f32_16x16x32_bf16 v[32:35], v[176:179], v[224:227], v[32:35]
	s_barrier
	s_branch .Lc0r_tail
.LBB0_382:
	s_cmp_eq_u32 s78, 0
	s_cbranch_scc1 .Lc0r_first
	s_cmp_eq_u32 s78, s52
	s_cbranch_scc0 .Lc0r_norm
	s_cmp_eq_u64 s[4:5], 0
	s_cbranch_scc1 .Lc0r_final
	s_branch .Lc0r_last
.Lc0r_norm:
	s_add_i32 s81, s64, 0x80
	s_and_b64 s[10:11], s[10:11], exec
	s_cselect_b32 s84, s24, s81
	s_cselect_b32 s85, s25, s65
	s_add_i32 s10, 0, 0x10000
	v_add_u32_e32 v3, s10, v208
	v_add_u32_e32 v144, s10, v209
	s_add_i32 s10, 0, 0x14000
	ds_read_b128 v[116:119], v3
	ds_read_b128 v[120:123], v3 offset:2048
	ds_read_b128 v[140:143], v144
	ds_read_b128 v[144:147], v144 offset:2048
	v_add_u32_e32 v3, s10, v208
	v_add_u32_e32 v176, s10, v209
	ds_read_b128 v[164:167], v3
	ds_read_b128 v[168:171], v3 offset:2048
	ds_read_b128 v[172:175], v176
	ds_read_b128 v[176:179], v176 offset:2048
	s_add_i32 s81, s84, 0x80
	s_add_i32 s82, s85, 0x80
	s_add_i32 s10, s29, s64
	s_mov_b32 m0, s53
	ds_read_b128 v[180:183], v214
	ds_read_b128 v[184:187], v214 offset:2048
	ds_read_b128 v[188:191], v215
	ds_read_b128 v[192:195], v215 offset:2048
	ds_read_b128 v[196:199], v214 offset:4096
	ds_read_b128 v[216:219], v214 offset:6144
	ds_read_b128 v[220:223], v215 offset:4096
	ds_read_b128 v[224:227], v215 offset:6144
	buffer_load_dwordx4 v204, s[48:51], s10 offen lds
	s_mov_b32 m0, s54
	s_nop 0
	buffer_load_dwordx4 v206, s[48:51], s10 offen lds
	s_waitcnt vmcnt(8)
	s_waitcnt lgkmcnt(0)
	s_barrier
	s_waitcnt lgkmcnt(0)
	v_mfma_f32_16x16x32_bf16 v[160:163], v[116:119], v[180:183], v[160:163]
	v_mfma_f32_16x16x32_bf16 v[152:155], v[120:123], v[180:183], v[152:155]
	v_mfma_f32_16x16x32_bf16 v[132:135], v[116:119], v[184:187], v[132:135]
	v_mfma_f32_16x16x32_bf16 v[124:127], v[120:123], v[184:187], v[124:127]
	v_mfma_f32_16x16x32_bf16 v[108:111], v[116:119], v[196:199], v[108:111]
	v_mfma_f32_16x16x32_bf16 v[100:103], v[120:123], v[196:199], v[100:103]
	v_mfma_f32_16x16x32_bf16 v[92:95], v[116:119], v[216:219], v[92:95]
	v_mfma_f32_16x16x32_bf16 v[84:87], v[120:123], v[216:219], v[84:87]
	v_mfma_f32_16x16x32_bf16 v[160:163], v[140:143], v[188:191], v[160:163]
	v_mfma_f32_16x16x32_bf16 v[152:155], v[144:147], v[188:191], v[152:155]
	v_mfma_f32_16x16x32_bf16 v[132:135], v[140:143], v[192:195], v[132:135]
	v_mfma_f32_16x16x32_bf16 v[124:127], v[144:147], v[192:195], v[124:127]
	v_mfma_f32_16x16x32_bf16 v[108:111], v[140:143], v[220:223], v[108:111]
	v_mfma_f32_16x16x32_bf16 v[100:103], v[144:147], v[220:223], v[100:103]
	v_mfma_f32_16x16x32_bf16 v[92:95], v[140:143], v[224:227], v[92:95]
	v_mfma_f32_16x16x32_bf16 v[84:87], v[144:147], v[224:227], v[84:87]
	v_mfma_f32_16x16x32_bf16 v[156:159], v[164:167], v[180:183], v[156:159]
	v_mfma_f32_16x16x32_bf16 v[148:151], v[168:171], v[180:183], v[148:151]
	v_mfma_f32_16x16x32_bf16 v[136:139], v[164:167], v[184:187], v[136:139]
	v_mfma_f32_16x16x32_bf16 v[128:131], v[168:171], v[184:187], v[128:131]
	v_mfma_f32_16x16x32_bf16 v[112:115], v[164:167], v[196:199], v[112:115]
	v_mfma_f32_16x16x32_bf16 v[104:107], v[168:171], v[196:199], v[104:107]
	v_mfma_f32_16x16x32_bf16 v[96:99], v[164:167], v[216:219], v[96:99]
	v_mfma_f32_16x16x32_bf16 v[88:91], v[168:171], v[216:219], v[88:91]
	v_mfma_f32_16x16x32_bf16 v[156:159], v[172:175], v[188:191], v[156:159]
	v_mfma_f32_16x16x32_bf16 v[148:151], v[176:179], v[188:191], v[148:151]
	v_mfma_f32_16x16x32_bf16 v[136:139], v[172:175], v[192:195], v[136:139]
	v_mfma_f32_16x16x32_bf16 v[128:131], v[176:179], v[192:195], v[128:131]
	v_mfma_f32_16x16x32_bf16 v[112:115], v[172:175], v[220:223], v[112:115]
	v_mfma_f32_16x16x32_bf16 v[104:107], v[176:179], v[220:223], v[104:107]
	v_mfma_f32_16x16x32_bf16 v[96:99], v[172:175], v[224:227], v[96:99]
	v_mfma_f32_16x16x32_bf16 v[88:91], v[176:179], v[224:227], v[88:91]
	s_barrier
	s_mov_b32 m0, s34
	s_mov_b32 s10, s50
	s_mov_b32 s11, s51
	ds_read_b128 v[180:183], v214 offset:16384
	ds_read_b128 v[184:187], v214 offset:18432
	ds_read_b128 v[188:191], v215 offset:16384
	ds_read_b128 v[192:195], v215 offset:18432
	ds_read_b128 v[196:199], v214 offset:20480
	ds_read_b128 v[216:219], v214 offset:22528
	ds_read_b128 v[220:223], v215 offset:20480
	ds_read_b128 v[224:227], v215 offset:22528
	buffer_load_dwordx4 v205, s[8:11], s85 offen lds
	s_mov_b32 m0, s35
	s_nop 0
	buffer_load_dwordx4 v207, s[8:11], s85 offen lds
	s_add_i32 s85, s85, s29
	s_mov_b32 m0, s36
	s_nop 0
	buffer_load_dwordx4 v205, s[8:11], s85 offen lds
	s_mov_b32 m0, s37
	s_nop 0
	buffer_load_dwordx4 v207, s[8:11], s85 offen lds
	s_mov_b32 m0, s31
	s_nop 0
	buffer_load_dwordx4 v204, s[48:51], s84 offen lds
	s_mov_b32 m0, s38
	s_nop 0
	buffer_load_dwordx4 v206, s[48:51], s84 offen lds
	s_waitcnt vmcnt(8)
	s_waitcnt lgkmcnt(0)
	s_barrier
	s_waitcnt lgkmcnt(0)
	v_mfma_f32_16x16x32_bf16 v[76:79], v[116:119], v[180:183], v[76:79]
	v_mfma_f32_16x16x32_bf16 v[68:71], v[120:123], v[180:183], v[68:71]
	v_mfma_f32_16x16x32_bf16 v[60:63], v[116:119], v[184:187], v[60:63]
	v_mfma_f32_16x16x32_bf16 v[52:55], v[120:123], v[184:187], v[52:55]
	v_mfma_f32_16x16x32_bf16 v[44:47], v[116:119], v[196:199], v[44:47]
	v_mfma_f32_16x16x32_bf16 v[36:39], v[120:123], v[196:199], v[36:39]
	v_mfma_f32_16x16x32_bf16 v[24:27], v[116:119], v[216:219], v[24:27]
	v_mfma_f32_16x16x32_bf16 v[20:23], v[120:123], v[216:219], v[20:23]
	v_mfma_f32_16x16x32_bf16 v[76:79], v[140:143], v[188:191], v[76:79]
	v_mfma_f32_16x16x32_bf16 v[68:71], v[144:147], v[188:191], v[68:71]
	v_mfma_f32_16x16x32_bf16 v[60:63], v[140:143], v[192:195], v[60:63]
	v_mfma_f32_16x16x32_bf16 v[52:55], v[144:147], v[192:195], v[52:55]
	v_mfma_f32_16x16x32_bf16 v[44:47], v[140:143], v[220:223], v[44:47]
	v_mfma_f32_16x16x32_bf16 v[36:39], v[144:147], v[220:223], v[36:39]
	v_mfma_f32_16x16x32_bf16 v[24:27], v[140:143], v[224:227], v[24:27]
	v_mfma_f32_16x16x32_bf16 v[20:23], v[144:147], v[224:227], v[20:23]
	v_mfma_f32_16x16x32_bf16 v[80:83], v[164:167], v[180:183], v[80:83]
	v_mfma_f32_16x16x32_bf16 v[72:75], v[168:171], v[180:183], v[72:75]
	v_mfma_f32_16x16x32_bf16 v[64:67], v[164:167], v[184:187], v[64:67]
	v_mfma_f32_16x16x32_bf16 v[56:59], v[168:171], v[184:187], v[56:59]
	v_mfma_f32_16x16x32_bf16 v[48:51], v[164:167], v[196:199], v[48:51]
	v_mfma_f32_16x16x32_bf16 v[40:43], v[168:171], v[196:199], v[40:43]
	v_mfma_f32_16x16x32_bf16 v[28:31], v[164:167], v[216:219], v[28:31]
	v_mfma_f32_16x16x32_bf16 v[32:35], v[168:171], v[216:219], v[32:35]
	v_mfma_f32_16x16x32_bf16 v[80:83], v[172:175], v[188:191], v[80:83]
	v_mfma_f32_16x16x32_bf16 v[72:75], v[176:179], v[188:191], v[72:75]
	v_mfma_f32_16x16x32_bf16 v[64:67], v[172:175], v[192:195], v[64:67]
	v_mfma_f32_16x16x32_bf16 v[56:59], v[176:179], v[192:195], v[56:59]
	v_mfma_f32_16x16x32_bf16 v[48:51], v[172:175], v[220:223], v[48:51]
	v_mfma_f32_16x16x32_bf16 v[40:43], v[176:179], v[220:223], v[40:43]
	v_mfma_f32_16x16x32_bf16 v[28:31], v[172:175], v[224:227], v[28:31]
	v_mfma_f32_16x16x32_bf16 v[32:35], v[176:179], v[224:227], v[32:35]
	s_barrier
	s_add_i32 s85, 0, 0x18000
	v_add_u32_e32 v3, s85, v208
	v_add_u32_e32 v144, s85, v209
	s_add_i32 s85, 0, 0x1c000
	ds_read_b128 v[116:119], v3
	ds_read_b128 v[120:123], v3 offset:2048
	ds_read_b128 v[140:143], v144
	ds_read_b128 v[144:147], v144 offset:2048
	v_add_u32_e32 v3, s85, v208
	v_add_u32_e32 v176, s85, v209
	ds_read_b128 v[164:167], v3
	ds_read_b128 v[168:171], v3 offset:2048
	ds_read_b128 v[172:175], v176
	ds_read_b128 v[176:179], v176 offset:2048
	s_add_i32 s84, s84, s29
	s_mov_b32 m0, s39
	ds_read_b128 v[180:183], v214 offset:32768
	ds_read_b128 v[184:187], v214 offset:34816
	ds_read_b128 v[188:191], v215 offset:32768
	ds_read_b128 v[192:195], v215 offset:34816
	ds_read_b128 v[196:199], v214 offset:36864
	ds_read_b128 v[216:219], v214 offset:38912
	ds_read_b128 v[220:223], v215 offset:36864
	ds_read_b128 v[224:227], v215 offset:38912
	buffer_load_dwordx4 v204, s[48:51], s84 offen lds
	s_mov_b32 m0, s40
	s_nop 0
	buffer_load_dwordx4 v206, s[48:51], s84 offen lds
	s_waitcnt vmcnt(8)
	s_waitcnt lgkmcnt(0)
	s_barrier
	s_waitcnt lgkmcnt(0)
	v_mfma_f32_16x16x32_bf16 v[160:163], v[116:119], v[180:183], v[160:163]
	v_mfma_f32_16x16x32_bf16 v[152:155], v[120:123], v[180:183], v[152:155]
	v_mfma_f32_16x16x32_bf16 v[132:135], v[116:119], v[184:187], v[132:135]
	v_mfma_f32_16x16x32_bf16 v[124:127], v[120:123], v[184:187], v[124:127]
	v_mfma_f32_16x16x32_bf16 v[108:111], v[116:119], v[196:199], v[108:111]
	v_mfma_f32_16x16x32_bf16 v[100:103], v[120:123], v[196:199], v[100:103]
	v_mfma_f32_16x16x32_bf16 v[92:95], v[116:119], v[216:219], v[92:95]
	v_mfma_f32_16x16x32_bf16 v[84:87], v[120:123], v[216:219], v[84:87]
	v_mfma_f32_16x16x32_bf16 v[160:163], v[140:143], v[188:191], v[160:163]
	v_mfma_f32_16x16x32_bf16 v[152:155], v[144:147], v[188:191], v[152:155]
	v_mfma_f32_16x16x32_bf16 v[132:135], v[140:143], v[192:195], v[132:135]
	v_mfma_f32_16x16x32_bf16 v[124:127], v[144:147], v[192:195], v[124:127]
	v_mfma_f32_16x16x32_bf16 v[108:111], v[140:143], v[220:223], v[108:111]
	v_mfma_f32_16x16x32_bf16 v[100:103], v[144:147], v[220:223], v[100:103]
	v_mfma_f32_16x16x32_bf16 v[92:95], v[140:143], v[224:227], v[92:95]
	v_mfma_f32_16x16x32_bf16 v[84:87], v[144:147], v[224:227], v[84:87]
	v_mfma_f32_16x16x32_bf16 v[156:159], v[164:167], v[180:183], v[156:159]
	v_mfma_f32_16x16x32_bf16 v[148:151], v[168:171], v[180:183], v[148:151]
	v_mfma_f32_16x16x32_bf16 v[136:139], v[164:167], v[184:187], v[136:139]
	v_mfma_f32_16x16x32_bf16 v[128:131], v[168:171], v[184:187], v[128:131]
	v_mfma_f32_16x16x32_bf16 v[112:115], v[164:167], v[196:199], v[112:115]
	v_mfma_f32_16x16x32_bf16 v[104:107], v[168:171], v[196:199], v[104:107]
	v_mfma_f32_16x16x32_bf16 v[96:99], v[164:167], v[216:219], v[96:99]
	v_mfma_f32_16x16x32_bf16 v[88:91], v[168:171], v[216:219], v[88:91]
	v_mfma_f32_16x16x32_bf16 v[156:159], v[172:175], v[188:191], v[156:159]
	v_mfma_f32_16x16x32_bf16 v[148:151], v[176:179], v[188:191], v[148:151]
	v_mfma_f32_16x16x32_bf16 v[136:139], v[172:175], v[192:195], v[136:139]
	v_mfma_f32_16x16x32_bf16 v[128:131], v[176:179], v[192:195], v[128:131]
	v_mfma_f32_16x16x32_bf16 v[112:115], v[172:175], v[220:223], v[112:115]
	v_mfma_f32_16x16x32_bf16 v[104:107], v[176:179], v[220:223], v[104:107]
	v_mfma_f32_16x16x32_bf16 v[96:99], v[172:175], v[224:227], v[96:99]
	v_mfma_f32_16x16x32_bf16 v[88:91], v[176:179], v[224:227], v[88:91]
	s_barrier
	s_mov_b32 m0, s41
	ds_read_b128 v[180:183], v214 offset:49152
	ds_read_b128 v[184:187], v214 offset:51200
	ds_read_b128 v[188:191], v215 offset:49152
	ds_read_b128 v[192:195], v215 offset:51200
	ds_read_b128 v[196:199], v214 offset:53248
	ds_read_b128 v[216:219], v214 offset:55296
	ds_read_b128 v[220:223], v215 offset:53248
	ds_read_b128 v[224:227], v215 offset:55296
	buffer_load_dwordx4 v205, s[8:11], s82 offen lds
	s_mov_b32 m0, s42
	s_nop 0
	buffer_load_dwordx4 v207, s[8:11], s82 offen lds
	s_add_i32 s82, s82, s29
	s_mov_b32 m0, s45
	s_nop 0
	buffer_load_dwordx4 v205, s[8:11], s82 offen lds
	s_mov_b32 m0, s46
	s_nop 0
	buffer_load_dwordx4 v207, s[8:11], s82 offen lds
	s_mov_b32 m0, s43
	s_nop 0
	buffer_load_dwordx4 v204, s[48:51], s81 offen lds
	s_mov_b32 m0, s44
	s_nop 0
	buffer_load_dwordx4 v206, s[48:51], s81 offen lds
	s_waitcnt vmcnt(8)
	s_waitcnt lgkmcnt(0)
	s_barrier
	s_waitcnt lgkmcnt(0)
	v_mfma_f32_16x16x32_bf16 v[76:79], v[116:119], v[180:183], v[76:79]
	v_mfma_f32_16x16x32_bf16 v[68:71], v[120:123], v[180:183], v[68:71]
	v_mfma_f32_16x16x32_bf16 v[60:63], v[116:119], v[184:187], v[60:63]
	v_mfma_f32_16x16x32_bf16 v[52:55], v[120:123], v[184:187], v[52:55]
	v_mfma_f32_16x16x32_bf16 v[44:47], v[116:119], v[196:199], v[44:47]
	v_mfma_f32_16x16x32_bf16 v[36:39], v[120:123], v[196:199], v[36:39]
	v_mfma_f32_16x16x32_bf16 v[24:27], v[116:119], v[216:219], v[24:27]
	v_mfma_f32_16x16x32_bf16 v[20:23], v[120:123], v[216:219], v[20:23]
	v_mfma_f32_16x16x32_bf16 v[76:79], v[140:143], v[188:191], v[76:79]
	v_mfma_f32_16x16x32_bf16 v[68:71], v[144:147], v[188:191], v[68:71]
	v_mfma_f32_16x16x32_bf16 v[60:63], v[140:143], v[192:195], v[60:63]
	v_mfma_f32_16x16x32_bf16 v[52:55], v[144:147], v[192:195], v[52:55]
	v_mfma_f32_16x16x32_bf16 v[44:47], v[140:143], v[220:223], v[44:47]
	v_mfma_f32_16x16x32_bf16 v[36:39], v[144:147], v[220:223], v[36:39]
	v_mfma_f32_16x16x32_bf16 v[24:27], v[140:143], v[224:227], v[24:27]
	v_mfma_f32_16x16x32_bf16 v[20:23], v[144:147], v[224:227], v[20:23]
	v_mfma_f32_16x16x32_bf16 v[80:83], v[164:167], v[180:183], v[80:83]
	v_mfma_f32_16x16x32_bf16 v[72:75], v[168:171], v[180:183], v[72:75]
	v_mfma_f32_16x16x32_bf16 v[64:67], v[164:167], v[184:187], v[64:67]
	v_mfma_f32_16x16x32_bf16 v[56:59], v[168:171], v[184:187], v[56:59]
	v_mfma_f32_16x16x32_bf16 v[48:51], v[164:167], v[196:199], v[48:51]
	v_mfma_f32_16x16x32_bf16 v[40:43], v[168:171], v[196:199], v[40:43]
	v_mfma_f32_16x16x32_bf16 v[28:31], v[164:167], v[216:219], v[28:31]
	v_mfma_f32_16x16x32_bf16 v[32:35], v[168:171], v[216:219], v[32:35]
	v_mfma_f32_16x16x32_bf16 v[80:83], v[172:175], v[188:191], v[80:83]
	v_mfma_f32_16x16x32_bf16 v[72:75], v[176:179], v[188:191], v[72:75]
	v_mfma_f32_16x16x32_bf16 v[64:67], v[172:175], v[192:195], v[64:67]
	v_mfma_f32_16x16x32_bf16 v[56:59], v[176:179], v[192:195], v[56:59]
	v_mfma_f32_16x16x32_bf16 v[48:51], v[172:175], v[220:223], v[48:51]
	v_mfma_f32_16x16x32_bf16 v[40:43], v[176:179], v[220:223], v[40:43]
	v_mfma_f32_16x16x32_bf16 v[28:31], v[172:175], v[224:227], v[28:31]
	v_mfma_f32_16x16x32_bf16 v[32:35], v[176:179], v[224:227], v[32:35]
	s_barrier
